# merged phases: GU/DN/OUT K-loop uses 32 MFMA per barrier pair (4 epochs per K-tile instead of 8), lgkmcnt(0) before each barrier, uniform vmcnt(8)
# speedup vs baseline: 1.0121x; 1.0085x over previous
; #define BAR() { __builtin_amdgcn_sched_barrier(0); __builtin_amdgcn_s_barrier(); asm volatile("" ::: "memory"); __builtin_amdgcn_sched_barrier(0); }
; DI void gemm_stream2(const bf16_t* __restrict__ A, int lda, const bf16_t* __restrict__ Bt, int ldb, int K, int m0, int n0, ...
;     ...
;     const int wave = __builtin_amdgcn_readfirstlane(tid >> 6), lane = tid & 63, wm = wave >> 1, wn = wave & 1, r = lane & 15, q = lane >> 4;
;     const int sc0 = ((lane & 7) ^ (lane >> 4)) * 8, sc1 = ((lane & 7) ^ (4 | (lane >> 4))) * 8;
;     const bf16_t* ga = A + (size_t)(m0 + wave * 32 + (lane >> 3)) * lda;
;     const bf16_t* gb = Bt + (size_t)(n0 + wave * 16 + (lane >> 3)) * ldb;
;     const bf16_t* gan = An + (size_t)(m0n + wave * 32 + (lane >> 3)) * ldan;
;     const bf16_t* gbn = Btn + (size_t)(n0n + wave * 16 + (lane >> 3)) * ldbn;
;     const unsigned wa = (unsigned)wave * 4096u, wbb = 32768u + (unsigned)wave * 2048u;
;     ...
;     const int sw = r >> 1;
;     const unsigned fo0 = (unsigned)(r * 128 + ((q ^ sw) << 4)), fo1 = (unsigned)(r * 128 + (((q ^ sw) ^ 4) << 4));
;     const unsigned aoff = (unsigned)(wm * 64) * 128u, boff = 32768u + (unsigned)(wn * 64) * 128u;
;     const int nk = K / 64;
;     const int grp = wave >> 2;
;     ...
;     int st = rg.st;
;     if (!rg.primed) {
;         const int s1p = st == 2 ? 0 : st + 1;
;         BAR();
;         STAGE(st, 0);
;         STAGE(s1p, 1);
;         asm volatile("s_waitcnt vmcnt(6)" ::: "memory");
;         BAR();
;     }
;     if (grp == 1) BAR();
.Lgu_ranged:
	s_cmp_ge_u32 s51, s52
	s_cbranch_scc1 .LBB0_860
	v_and_b32_e32 v190, 63, v193
	v_and_b32_e32 v191, 15, v190
	v_lshrrev_b32_e32 v17, 4, v190
	v_lshrrev_b32_e32 v18, 3, v190
	v_and_b32_e32 v19, 7, v190
	v_xor_b32_e32 v195, v19, v17
	v_lshlrev_b32_e32 v195, 4, v195
	v_lshl_add_u32 v184, v18, 11, v195
	v_or_b32_e32 v195, 4, v17
	v_xor_b32_e32 v195, v19, v195
	v_lshlrev_b32_e32 v195, 4, v195
	v_add_u32_e32 v227, 8, v18
	v_lshl_add_u32 v185, v227, 11, v195
	v_lshrrev_b32_e32 v195, 1, v191
	v_xor_b32_e32 v195, v17, v195
	v_lshlrev_b32_e32 v195, 4, v195
	s_lshl_b32 s1, s33, 6
	v_add_u32_e32 v227, s1, v191
	v_lshl_add_u32 v186, v227, 7, v195
	v_xor_b32_e32 v187, 64, v186
	v_mul_u32_u24_e32 v228, 0x1600, v227
	s_lshl_b32 s1, s36, 5
	v_add_u32_e32 v227, s1, v191
	v_lshl_add_u32 v188, v227, 7, v195
	v_add_u32_e32 v188, 0x10000, v188
	v_xor_b32_e32 v189, 64, v188
	v_lshl_add_u32 v229, v17, 3, s1
	v_add_u32_e32 v237, v228, v229
	s_mul_i32 s1, s51, 0x1745e
	s_lshr_b32 s2, s1, 24
	s_mul_i32 s1, s2, 0xb0
	s_sub_u32 s1, s51, s1
	s_lshr_b32 s3, s1, 3
	s_and_b32 s37, s1, 7
	s_cmp_lt_u32 s2, 8
	s_cselect_b32 s58, s3, s1
	s_cselect_b32 s37, s37, 0
	s_lshl_b32 s2, s2, 3
	s_add_i32 s57, s2, s37
	s_lshl_b32 s1, s57, 19
	s_lshl_b32 s2, s10, 15
	s_add_u32 s1, s1, s2
	s_add_u32 s1, s1, 0x3240000
	s_add_u32 s66, s88, s1
	s_addc_u32 s67, s89, 0
	s_add_u32 s68, s66, 0x40000
	s_addc_u32 s69, s67, 0
	s_lshl_b32 s1, s58, 19
	s_add_u32 s1, s1, s2
	s_add_u32 s1, s1, s61
	s_add_u32 s70, s88, s1
	s_addc_u32 s71, s89, 0
	s_add_u32 s72, s70, 0x40000
	s_addc_u32 s73, s71, 0
	s_add_i32 m0, s39, 0x10000
	s_nop 0
	global_load_lds_dwordx4 v184, s[70:71]
	s_add_i32 m0, s39, 0x10400
	s_nop 0
	global_load_lds_dwordx4 v185, s[70:71]
	s_add_u32 s70, s70, 0x80
	s_addc_u32 s71, s71, 0
	s_add_i32 m0, s39, 0x0
	s_nop 0
	global_load_lds_dwordx4 v184, s[66:67]
	s_add_i32 m0, s39, 0x400
	s_nop 0
	global_load_lds_dwordx4 v185, s[66:67]
	s_add_u32 s66, s66, 0x80
	s_addc_u32 s67, s67, 0
	s_add_i32 m0, s39, 0x14000
	s_nop 0
	global_load_lds_dwordx4 v184, s[72:73]
	s_add_i32 m0, s39, 0x14400
	s_nop 0
	global_load_lds_dwordx4 v185, s[72:73]
	s_add_u32 s72, s72, 0x80
	s_addc_u32 s73, s73, 0
	s_add_i32 m0, s39, 0x4000
	s_nop 0
	global_load_lds_dwordx4 v184, s[68:69]
	s_add_i32 m0, s39, 0x4400
	s_nop 0
	global_load_lds_dwordx4 v185, s[68:69]
	s_add_u32 s68, s68, 0x80
	s_addc_u32 s69, s69, 0
	s_add_i32 m0, s39, 0x18000
	s_nop 0
	global_load_lds_dwordx4 v184, s[70:71]
	s_add_i32 m0, s39, 0x18400
	s_nop 0
	global_load_lds_dwordx4 v185, s[70:71]
	s_add_u32 s70, s70, 0x80
	s_addc_u32 s71, s71, 0
	s_add_i32 m0, s39, 0x8000
	s_nop 0
	global_load_lds_dwordx4 v184, s[66:67]
	s_add_i32 m0, s39, 0x8400
	s_nop 0
	global_load_lds_dwordx4 v185, s[66:67]
	s_add_u32 s66, s66, 0x80
	s_addc_u32 s67, s67, 0
	s_add_i32 m0, s39, 0x1c000
	s_nop 0
	global_load_lds_dwordx4 v184, s[72:73]
	s_add_i32 m0, s39, 0x1c400
	s_nop 0
	global_load_lds_dwordx4 v185, s[72:73]
	s_add_u32 s72, s72, 0x80
	s_addc_u32 s73, s73, 0
	s_waitcnt vmcnt(8)
	s_barrier
	s_cmp_eq_u32 s33, 0
	s_cbranch_scc1 .Lgu_lead
	s_barrier
.Lgu_lead:
.Lgu_tile:
	s_add_u32 s76, s51, s53
	s_cmp_lt_u32 s76, s52
	s_cselect_b32 s54, 1, 0
	s_cbranch_scc0 .Lgu_nonext
	s_mul_i32 s1, s76, 0x1745e
	s_lshr_b32 s2, s1, 24
	s_mul_i32 s1, s2, 0xb0
	s_sub_u32 s1, s76, s1
	s_lshr_b32 s3, s1, 3
	s_and_b32 s37, s1, 7
	s_cmp_lt_u32 s2, 8
	s_cselect_b32 s60, s3, s1
	s_cselect_b32 s37, s37, 0
	s_lshl_b32 s2, s2, 3
	s_add_i32 s59, s2, s37
	s_lshl_b32 s1, s59, 19
	s_lshl_b32 s2, s10, 15
	s_add_u32 s1, s1, s2
	s_add_u32 s1, s1, 0x3240000
	s_add_u32 s74, s88, s1
	s_addc_u32 s75, s89, 0
	s_add_u32 s78, s74, 0x40000
	s_addc_u32 s79, s75, 0
	s_lshl_b32 s1, s60, 19
	s_add_u32 s1, s1, s2
	s_add_u32 s1, s1, s61
	s_add_u32 s80, s88, s1
	s_addc_u32 s81, s89, 0
	s_add_u32 s82, s80, 0x40000
	s_addc_u32 s83, s81, 0

; #define LAS __attribute__((address_space(3)))
; #define BAR() { __builtin_amdgcn_sched_barrier(0); __builtin_amdgcn_s_barrier(); asm volatile("" ::: "memory"); __builtin_amdgcn_sched_barrier(0); }
; DI void gemm_stream2(const bf16_t* __restrict__ A, int lda, const bf16_t* __restrict__ Bt, int ldb, int K, int m0, int n0, ...
;     ...
;     for (int kt = 0; kt < nk; ++kt) {
;         const bool pf = (kt + 2 < nk) || has_next, more = (kt + 1 < nk) || has_next;
;         const bf16_t* pa = (kt + 2 < nk) ? ga + (kt + 2) * 64 : gan + (kt + 2 - nk) * 64;
;         const bf16_t* pb = (kt + 2 < nk) ? gb + (kt + 2) * 64 : gbn + (kt + 2 - nk) * 64;
;         const int plda = (kt + 2 < nk) ? lda : ldan, pldb = (kt + 2 < nk) ? ldb : ldbn;
;         const int s2 = st >= 1 ? st - 1 : 2;
;         const LAS char* base = lds + st * 49152;
; #pragma unroll
;         for (int ks = 0; ks < 2; ++ks) {
;             const unsigned fo = ks ? fo1 : fo0;
;             bf16x8 af[4], bfr[4];
; #pragma unroll
;             for (int i = 0; i < 4; ++i) { af[i] = *(const LAS bf16x8*)(base + aoff + i * 2048 + fo); bfr[i] = *(const LAS bf16x8*)(base + boff + i * 2048 + fo); }
;             if (ks == 1 && more) { if (pf) asm volatile("s_waitcnt vmcnt(3)" ::: "memory"); else asm volatile("s_waitcnt vmcnt(0)" ::: "memory"); }
;             if (pf) { PIECE(s2, ks * 3 + 0); PIECE(s2, ks * 3 + 1); PIECE(s2, ks * 3 + 2); }
;             asm volatile("s_waitcnt lgkmcnt(0)" ::: "memory");
;             BAR();
;             __builtin_amdgcn_s_setprio(1);
; #pragma unroll
;             for (int mi = 0; mi < 4; ++mi)
; #pragma unroll
;                 for (int ni = 0; ni < 4; ++ni) acc[mi][ni] = __builtin_amdgcn_mfma_f32_16x16x32_bf16(bfr[ni], af[mi], acc[mi][ni], 0, 0, 0);
;             __builtin_amdgcn_s_setprio(0);
;             BAR();
;         }
;         st = st == 2 ? 0 : st + 1;
;     }
.Lgu_kloop:
	ds_read_b128 v[0:3], v188 offset:16
	ds_read_b128 v[4:7], v189 offset:16
	ds_read_b128 v[8:11], v188 offset:2064
	ds_read_b128 v[12:15], v189 offset:2064
	ds_read_b128 v[196:199], v188 offset:16400
	ds_read_b128 v[200:203], v189 offset:16400
	ds_read_b128 v[204:207], v188 offset:18448
	ds_read_b128 v[208:211], v189 offset:18448
	ds_read_b128 v[152:155], v186 offset:16
	ds_read_b128 v[156:159], v187 offset:16
	ds_read_b128 v[160:163], v186 offset:2064
	ds_read_b128 v[164:167], v187 offset:2064
	ds_read_b128 v[168:171], v186 offset:4112
	ds_read_b128 v[172:175], v187 offset:4112
	ds_read_b128 v[176:179], v186 offset:6160
	ds_read_b128 v[180:183], v187 offset:6160
	s_add_i32 m0, s39, 0xc000
	s_nop 0
	global_load_lds_dwordx4 v184, s[68:69]
	s_add_i32 m0, s39, 0xc400
	s_nop 0
	global_load_lds_dwordx4 v185, s[68:69]
	s_add_u32 s68, s68, 0x80
	s_addc_u32 s69, s69, 0
	s_waitcnt lgkmcnt(0)
	s_waitcnt vmcnt(8)
	s_barrier
	s_setprio 1
	v_mfma_f32_16x16x32_bf16 v[24:27], v[0:3], v[152:155], v[24:27]
	v_mfma_f32_16x16x32_bf16 v[28:31], v[8:11], v[152:155], v[28:31]
	v_mfma_f32_16x16x32_bf16 v[32:35], v[0:3], v[160:163], v[32:35]
	v_mfma_f32_16x16x32_bf16 v[36:39], v[8:11], v[160:163], v[36:39]
	v_mfma_f32_16x16x32_bf16 v[40:43], v[0:3], v[168:171], v[40:43]
	v_mfma_f32_16x16x32_bf16 v[44:47], v[8:11], v[168:171], v[44:47]
	v_mfma_f32_16x16x32_bf16 v[48:51], v[0:3], v[176:179], v[48:51]
	v_mfma_f32_16x16x32_bf16 v[52:55], v[8:11], v[176:179], v[52:55]
	v_mfma_f32_16x16x32_bf16 v[24:27], v[4:7], v[156:159], v[24:27]
	v_mfma_f32_16x16x32_bf16 v[28:31], v[12:15], v[156:159], v[28:31]
	v_mfma_f32_16x16x32_bf16 v[32:35], v[4:7], v[164:167], v[32:35]
	v_mfma_f32_16x16x32_bf16 v[36:39], v[12:15], v[164:167], v[36:39]
	v_mfma_f32_16x16x32_bf16 v[40:43], v[4:7], v[172:175], v[40:43]
	v_mfma_f32_16x16x32_bf16 v[44:47], v[12:15], v[172:175], v[44:47]
	v_mfma_f32_16x16x32_bf16 v[48:51], v[4:7], v[180:183], v[48:51]
	v_mfma_f32_16x16x32_bf16 v[52:55], v[12:15], v[180:183], v[52:55]
	v_mfma_f32_16x16x32_bf16 v[56:59], v[196:199], v[152:155], v[56:59]
	v_mfma_f32_16x16x32_bf16 v[60:63], v[204:207], v[152:155], v[60:63]
	v_mfma_f32_16x16x32_bf16 v[64:67], v[196:199], v[160:163], v[64:67]
	v_mfma_f32_16x16x32_bf16 v[68:71], v[204:207], v[160:163], v[68:71]
	v_mfma_f32_16x16x32_bf16 v[72:75], v[196:199], v[168:171], v[72:75]
	v_mfma_f32_16x16x32_bf16 v[76:79], v[204:207], v[168:171], v[76:79]
	v_mfma_f32_16x16x32_bf16 v[80:83], v[196:199], v[176:179], v[80:83]
	v_mfma_f32_16x16x32_bf16 v[84:87], v[204:207], v[176:179], v[84:87]
	v_mfma_f32_16x16x32_bf16 v[56:59], v[200:203], v[156:159], v[56:59]
	v_mfma_f32_16x16x32_bf16 v[60:63], v[208:211], v[156:159], v[60:63]
	v_mfma_f32_16x16x32_bf16 v[64:67], v[200:203], v[164:167], v[64:67]
	v_mfma_f32_16x16x32_bf16 v[68:71], v[208:211], v[164:167], v[68:71]
	v_mfma_f32_16x16x32_bf16 v[72:75], v[200:203], v[172:175], v[72:75]
	v_mfma_f32_16x16x32_bf16 v[76:79], v[208:211], v[172:175], v[76:79]
	v_mfma_f32_16x16x32_bf16 v[80:83], v[200:203], v[180:183], v[80:83]
	v_mfma_f32_16x16x32_bf16 v[84:87], v[208:211], v[180:183], v[84:87]
	s_setprio 0
	s_barrier
	ds_read_b128 v[152:155], v186 offset:16400
	ds_read_b128 v[156:159], v187 offset:16400
	ds_read_b128 v[160:163], v186 offset:18448
	ds_read_b128 v[164:167], v187 offset:18448
	ds_read_b128 v[168:171], v186 offset:20496
	ds_read_b128 v[172:175], v187 offset:20496
	ds_read_b128 v[176:179], v186 offset:22544
	ds_read_b128 v[180:183], v187 offset:22544
	s_cmp_lg_u32 s0, s54
	s_cbranch_scc1 .Lgu_nosw1
	s_mov_b64 s[66:67], s[74:75]
	s_mov_b64 s[70:71], s[80:81]
	s_mov_b64 s[72:73], s[82:83]
.Lgu_nosw1:
	s_add_i32 m0, s39, 0x10000
	s_nop 0
	global_load_lds_dwordx4 v184, s[70:71]
	s_add_i32 m0, s39, 0x10400
	s_nop 0
	global_load_lds_dwordx4 v185, s[70:71]
	s_add_u32 s70, s70, 0x80
	s_addc_u32 s71, s71, 0
	s_add_i32 m0, s39, 0x0
	s_nop 0
	global_load_lds_dwordx4 v184, s[66:67]
	s_add_i32 m0, s39, 0x400
	s_nop 0
	global_load_lds_dwordx4 v185, s[66:67]
	s_add_u32 s66, s66, 0x80
	s_addc_u32 s67, s67, 0
	s_add_i32 m0, s39, 0x14000
	s_nop 0
	global_load_lds_dwordx4 v184, s[72:73]
	s_add_i32 m0, s39, 0x14400
	s_nop 0
	global_load_lds_dwordx4 v185, s[72:73]
	s_add_u32 s72, s72, 0x80
	s_addc_u32 s73, s73, 0
	s_waitcnt lgkmcnt(0)
	s_waitcnt vmcnt(8)
	s_barrier
	s_setprio 1
	v_mfma_f32_16x16x32_bf16 v[88:91], v[0:3], v[152:155], v[88:91]
	v_mfma_f32_16x16x32_bf16 v[92:95], v[8:11], v[152:155], v[92:95]
	v_mfma_f32_16x16x32_bf16 v[96:99], v[0:3], v[160:163], v[96:99]
	v_mfma_f32_16x16x32_bf16 v[100:103], v[8:11], v[160:163], v[100:103]
	v_mfma_f32_16x16x32_bf16 v[104:107], v[0:3], v[168:171], v[104:107]
	v_mfma_f32_16x16x32_bf16 v[108:111], v[8:11], v[168:171], v[108:111]
	v_mfma_f32_16x16x32_bf16 v[112:115], v[0:3], v[176:179], v[112:115]
	v_mfma_f32_16x16x32_bf16 v[116:119], v[8:11], v[176:179], v[116:119]
	v_mfma_f32_16x16x32_bf16 v[88:91], v[4:7], v[156:159], v[88:91]
	v_mfma_f32_16x16x32_bf16 v[92:95], v[12:15], v[156:159], v[92:95]
	v_mfma_f32_16x16x32_bf16 v[96:99], v[4:7], v[164:167], v[96:99]
	v_mfma_f32_16x16x32_bf16 v[100:103], v[12:15], v[164:167], v[100:103]
	v_mfma_f32_16x16x32_bf16 v[104:107], v[4:7], v[172:175], v[104:107]
	v_mfma_f32_16x16x32_bf16 v[108:111], v[12:15], v[172:175], v[108:111]
	v_mfma_f32_16x16x32_bf16 v[112:115], v[4:7], v[180:183], v[112:115]
	v_mfma_f32_16x16x32_bf16 v[116:119], v[12:15], v[180:183], v[116:119]
	v_mfma_f32_16x16x32_bf16 v[120:123], v[196:199], v[152:155], v[120:123]
	v_mfma_f32_16x16x32_bf16 v[124:127], v[204:207], v[152:155], v[124:127]
	v_mfma_f32_16x16x32_bf16 v[128:131], v[196:199], v[160:163], v[128:131]
	v_mfma_f32_16x16x32_bf16 v[132:135], v[204:207], v[160:163], v[132:135]
	v_mfma_f32_16x16x32_bf16 v[136:139], v[196:199], v[168:171], v[136:139]
	v_mfma_f32_16x16x32_bf16 v[140:143], v[204:207], v[168:171], v[140:143]
	v_mfma_f32_16x16x32_bf16 v[144:147], v[196:199], v[176:179], v[144:147]
	v_mfma_f32_16x16x32_bf16 v[148:151], v[204:207], v[176:179], v[148:151]
	v_mfma_f32_16x16x32_bf16 v[120:123], v[200:203], v[156:159], v[120:123]
	v_mfma_f32_16x16x32_bf16 v[124:127], v[208:211], v[156:159], v[124:127]
	v_mfma_f32_16x16x32_bf16 v[128:131], v[200:203], v[164:167], v[128:131]
	v_mfma_f32_16x16x32_bf16 v[132:135], v[208:211], v[164:167], v[132:135]
	v_mfma_f32_16x16x32_bf16 v[136:139], v[200:203], v[172:175], v[136:139]
	v_mfma_f32_16x16x32_bf16 v[140:143], v[208:211], v[172:175], v[140:143]
	v_mfma_f32_16x16x32_bf16 v[144:147], v[200:203], v[180:183], v[144:147]
	v_mfma_f32_16x16x32_bf16 v[148:151], v[208:211], v[180:183], v[148:151]
	s_setprio 0
	s_barrier
; #define LAS __attribute__((address_space(3)))
; #define BAR() { __builtin_amdgcn_sched_barrier(0); __builtin_amdgcn_s_barrier(); asm volatile("" ::: "memory"); __builtin_amdgcn_sched_barrier(0); }
; DI void gemm_stream2(const bf16_t* __restrict__ A, int lda, const bf16_t* __restrict__ Bt, int ldb, int K, int m0, int n0, ...
;     ...
;     for (int kt = 0; kt < nk; ++kt) {
;         const bool pf = (kt + 2 < nk) || has_next, more = (kt + 1 < nk) || has_next;
;         const bf16_t* pa = (kt + 2 < nk) ? ga + (kt + 2) * 64 : gan + (kt + 2 - nk) * 64;
;         const bf16_t* pb = (kt + 2 < nk) ? gb + (kt + 2) * 64 : gbn + (kt + 2 - nk) * 64;
;         const int plda = (kt + 2 < nk) ? lda : ldan, pldb = (kt + 2 < nk) ? ldb : ldbn;
;         const int s2 = st >= 1 ? st - 1 : 2;
;         const LAS char* base = lds + st * 49152;
; #pragma unroll
;         for (int ks = 0; ks < 2; ++ks) {
;             const unsigned fo = ks ? fo1 : fo0;
;             bf16x8 af[4], bfr[4];
; #pragma unroll
;             for (int i = 0; i < 4; ++i) { af[i] = *(const LAS bf16x8*)(base + aoff + i * 2048 + fo); bfr[i] = *(const LAS bf16x8*)(base + boff + i * 2048 + fo); }
;             if (ks == 1 && more) { if (pf) asm volatile("s_waitcnt vmcnt(3)" ::: "memory"); else asm volatile("s_waitcnt vmcnt(0)" ::: "memory"); }
;             if (pf) { PIECE(s2, ks * 3 + 0); PIECE(s2, ks * 3 + 1); PIECE(s2, ks * 3 + 2); }
;             asm volatile("s_waitcnt lgkmcnt(0)" ::: "memory");
;             BAR();
;             __builtin_amdgcn_s_setprio(1);
; #pragma unroll
;             for (int mi = 0; mi < 4; ++mi)
; #pragma unroll
;                 for (int ni = 0; ni < 4; ++ni) acc[mi][ni] = __builtin_amdgcn_mfma_f32_16x16x32_bf16(bfr[ni], af[mi], acc[mi][ni], 0, 0, 0);
;             __builtin_amdgcn_s_setprio(0);
;             BAR();
;         }
;         st = st == 2 ? 0 : st + 1;
;     }
	ds_read_b128 v[0:3], v188 offset:32784
	ds_read_b128 v[4:7], v189 offset:32784
	ds_read_b128 v[8:11], v188 offset:34832
	ds_read_b128 v[12:15], v189 offset:34832
	ds_read_b128 v[196:199], v188 offset:49168
	ds_read_b128 v[200:203], v189 offset:49168
	ds_read_b128 v[204:207], v188 offset:51216
	ds_read_b128 v[208:211], v189 offset:51216
	ds_read_b128 v[152:155], v186 offset:32784
	ds_read_b128 v[156:159], v187 offset:32784
	ds_read_b128 v[160:163], v186 offset:34832
	ds_read_b128 v[164:167], v187 offset:34832
	ds_read_b128 v[168:171], v186 offset:36880
	ds_read_b128 v[172:175], v187 offset:36880
	ds_read_b128 v[176:179], v186 offset:38928
	ds_read_b128 v[180:183], v187 offset:38928
	s_cmp_lg_u32 s0, s54
	s_cbranch_scc1 .Lgu_nosw2
	s_mov_b64 s[68:69], s[78:79]
.Lgu_nosw2:
	s_add_i32 m0, s39, 0x4000
	s_nop 0
	global_load_lds_dwordx4 v184, s[68:69]
	s_add_i32 m0, s39, 0x4400
	s_nop 0
	global_load_lds_dwordx4 v185, s[68:69]
	s_add_u32 s68, s68, 0x80
	s_addc_u32 s69, s69, 0
	s_waitcnt lgkmcnt(0)
	s_waitcnt vmcnt(8)
	s_barrier
	s_setprio 1
	v_mfma_f32_16x16x32_bf16 v[24:27], v[0:3], v[152:155], v[24:27]
	v_mfma_f32_16x16x32_bf16 v[28:31], v[8:11], v[152:155], v[28:31]
	v_mfma_f32_16x16x32_bf16 v[32:35], v[0:3], v[160:163], v[32:35]
	v_mfma_f32_16x16x32_bf16 v[36:39], v[8:11], v[160:163], v[36:39]
	v_mfma_f32_16x16x32_bf16 v[40:43], v[0:3], v[168:171], v[40:43]
	v_mfma_f32_16x16x32_bf16 v[44:47], v[8:11], v[168:171], v[44:47]
	v_mfma_f32_16x16x32_bf16 v[48:51], v[0:3], v[176:179], v[48:51]
	v_mfma_f32_16x16x32_bf16 v[52:55], v[8:11], v[176:179], v[52:55]
	v_mfma_f32_16x16x32_bf16 v[24:27], v[4:7], v[156:159], v[24:27]
	v_mfma_f32_16x16x32_bf16 v[28:31], v[12:15], v[156:159], v[28:31]
	v_mfma_f32_16x16x32_bf16 v[32:35], v[4:7], v[164:167], v[32:35]
	v_mfma_f32_16x16x32_bf16 v[36:39], v[12:15], v[164:167], v[36:39]
	v_mfma_f32_16x16x32_bf16 v[40:43], v[4:7], v[172:175], v[40:43]
	v_mfma_f32_16x16x32_bf16 v[44:47], v[12:15], v[172:175], v[44:47]
	v_mfma_f32_16x16x32_bf16 v[48:51], v[4:7], v[180:183], v[48:51]
	v_mfma_f32_16x16x32_bf16 v[52:55], v[12:15], v[180:183], v[52:55]
	v_mfma_f32_16x16x32_bf16 v[56:59], v[196:199], v[152:155], v[56:59]
	v_mfma_f32_16x16x32_bf16 v[60:63], v[204:207], v[152:155], v[60:63]
	v_mfma_f32_16x16x32_bf16 v[64:67], v[196:199], v[160:163], v[64:67]
	v_mfma_f32_16x16x32_bf16 v[68:71], v[204:207], v[160:163], v[68:71]
	v_mfma_f32_16x16x32_bf16 v[72:75], v[196:199], v[168:171], v[72:75]
	v_mfma_f32_16x16x32_bf16 v[76:79], v[204:207], v[168:171], v[76:79]
	v_mfma_f32_16x16x32_bf16 v[80:83], v[196:199], v[176:179], v[80:83]
	v_mfma_f32_16x16x32_bf16 v[84:87], v[204:207], v[176:179], v[84:87]
	v_mfma_f32_16x16x32_bf16 v[56:59], v[200:203], v[156:159], v[56:59]
	v_mfma_f32_16x16x32_bf16 v[60:63], v[208:211], v[156:159], v[60:63]
	v_mfma_f32_16x16x32_bf16 v[64:67], v[200:203], v[164:167], v[64:67]
	v_mfma_f32_16x16x32_bf16 v[68:71], v[208:211], v[164:167], v[68:71]
	v_mfma_f32_16x16x32_bf16 v[72:75], v[200:203], v[172:175], v[72:75]
	v_mfma_f32_16x16x32_bf16 v[76:79], v[208:211], v[172:175], v[76:79]
	v_mfma_f32_16x16x32_bf16 v[80:83], v[200:203], v[180:183], v[80:83]
	v_mfma_f32_16x16x32_bf16 v[84:87], v[208:211], v[180:183], v[84:87]
	s_setprio 0
	s_barrier
	ds_read_b128 v[152:155], v186 offset:49168
	ds_read_b128 v[156:159], v187 offset:49168
	ds_read_b128 v[160:163], v186 offset:51216
	ds_read_b128 v[164:167], v187 offset:51216
	ds_read_b128 v[168:171], v186 offset:53264
	ds_read_b128 v[172:175], v187 offset:53264
	ds_read_b128 v[176:179], v186 offset:55312
	ds_read_b128 v[180:183], v187 offset:55312
	s_add_i32 m0, s39, 0x18000
	s_nop 0
	global_load_lds_dwordx4 v184, s[70:71]
	s_add_i32 m0, s39, 0x18400
	s_nop 0
	global_load_lds_dwordx4 v185, s[70:71]
	s_add_u32 s70, s70, 0x80
	s_addc_u32 s71, s71, 0
	s_add_i32 m0, s39, 0x8000
	s_nop 0
	global_load_lds_dwordx4 v184, s[66:67]
	s_add_i32 m0, s39, 0x8400
	s_nop 0
	global_load_lds_dwordx4 v185, s[66:67]
	s_add_u32 s66, s66, 0x80
	s_addc_u32 s67, s67, 0
	s_add_i32 m0, s39, 0x1c000
	s_nop 0
	global_load_lds_dwordx4 v184, s[72:73]
	s_add_i32 m0, s39, 0x1c400
	s_nop 0
	global_load_lds_dwordx4 v185, s[72:73]
	s_add_u32 s72, s72, 0x80
	s_addc_u32 s73, s73, 0
	s_waitcnt lgkmcnt(0)
	s_waitcnt vmcnt(8)
	s_barrier
	s_setprio 1
	v_mfma_f32_16x16x32_bf16 v[88:91], v[0:3], v[152:155], v[88:91]
	v_mfma_f32_16x16x32_bf16 v[92:95], v[8:11], v[152:155], v[92:95]
	v_mfma_f32_16x16x32_bf16 v[96:99], v[0:3], v[160:163], v[96:99]
	v_mfma_f32_16x16x32_bf16 v[100:103], v[8:11], v[160:163], v[100:103]
	v_mfma_f32_16x16x32_bf16 v[104:107], v[0:3], v[168:171], v[104:107]
	v_mfma_f32_16x16x32_bf16 v[108:111], v[8:11], v[168:171], v[108:111]
	v_mfma_f32_16x16x32_bf16 v[112:115], v[0:3], v[176:179], v[112:115]
	v_mfma_f32_16x16x32_bf16 v[116:119], v[8:11], v[176:179], v[116:119]
	v_mfma_f32_16x16x32_bf16 v[88:91], v[4:7], v[156:159], v[88:91]
	v_mfma_f32_16x16x32_bf16 v[92:95], v[12:15], v[156:159], v[92:95]
	v_mfma_f32_16x16x32_bf16 v[96:99], v[4:7], v[164:167], v[96:99]
	v_mfma_f32_16x16x32_bf16 v[100:103], v[12:15], v[164:167], v[100:103]
	v_mfma_f32_16x16x32_bf16 v[104:107], v[4:7], v[172:175], v[104:107]
	v_mfma_f32_16x16x32_bf16 v[108:111], v[12:15], v[172:175], v[108:111]
	v_mfma_f32_16x16x32_bf16 v[112:115], v[4:7], v[180:183], v[112:115]
	v_mfma_f32_16x16x32_bf16 v[116:119], v[12:15], v[180:183], v[116:119]
	v_mfma_f32_16x16x32_bf16 v[120:123], v[196:199], v[152:155], v[120:123]
	v_mfma_f32_16x16x32_bf16 v[124:127], v[204:207], v[152:155], v[124:127]
	v_mfma_f32_16x16x32_bf16 v[128:131], v[196:199], v[160:163], v[128:131]
	v_mfma_f32_16x16x32_bf16 v[132:135], v[204:207], v[160:163], v[132:135]
	v_mfma_f32_16x16x32_bf16 v[136:139], v[196:199], v[168:171], v[136:139]
	v_mfma_f32_16x16x32_bf16 v[140:143], v[204:207], v[168:171], v[140:143]
	v_mfma_f32_16x16x32_bf16 v[144:147], v[196:199], v[176:179], v[144:147]
	v_mfma_f32_16x16x32_bf16 v[148:151], v[204:207], v[176:179], v[148:151]
	v_mfma_f32_16x16x32_bf16 v[120:123], v[200:203], v[156:159], v[120:123]
	v_mfma_f32_16x16x32_bf16 v[124:127], v[208:211], v[156:159], v[124:127]
	v_mfma_f32_16x16x32_bf16 v[128:131], v[200:203], v[164:167], v[128:131]
	v_mfma_f32_16x16x32_bf16 v[132:135], v[208:211], v[164:167], v[132:135]
	v_mfma_f32_16x16x32_bf16 v[136:139], v[200:203], v[172:175], v[136:139]
	v_mfma_f32_16x16x32_bf16 v[140:143], v[208:211], v[172:175], v[140:143]
	v_mfma_f32_16x16x32_bf16 v[144:147], v[200:203], v[180:183], v[144:147]
	v_mfma_f32_16x16x32_bf16 v[148:151], v[208:211], v[180:183], v[148:151]
	s_setprio 0
	s_barrier
; #define LAS __attribute__((address_space(3)))
; #define BAR() { __builtin_amdgcn_sched_barrier(0); __builtin_amdgcn_s_barrier(); asm volatile("" ::: "memory"); __builtin_amdgcn_sched_barrier(0); }
; DI void gemm_stream2(const bf16_t* __restrict__ A, int lda, const bf16_t* __restrict__ Bt, int ldb, int K, int m0, int n0, ...
;     ...
;     for (int kt = 0; kt < nk; ++kt) {
;         const bool pf = (kt + 2 < nk) || has_next, more = (kt + 1 < nk) || has_next;
;         const bf16_t* pa = (kt + 2 < nk) ? ga + (kt + 2) * 64 : gan + (kt + 2 - nk) * 64;
;         const bf16_t* pb = (kt + 2 < nk) ? gb + (kt + 2) * 64 : gbn + (kt + 2 - nk) * 64;
;         const int plda = (kt + 2 < nk) ? lda : ldan, pldb = (kt + 2 < nk) ? ldb : ldbn;
;         const int s2 = st >= 1 ? st - 1 : 2;
;         const LAS char* base = lds + st * 49152;
; #pragma unroll
;         for (int ks = 0; ks < 2; ++ks) {
;             const unsigned fo = ks ? fo1 : fo0;
;             bf16x8 af[4], bfr[4];
; #pragma unroll
;             for (int i = 0; i < 4; ++i) { af[i] = *(const LAS bf16x8*)(base + aoff + i * 2048 + fo); bfr[i] = *(const LAS bf16x8*)(base + boff + i * 2048 + fo); }
;             if (ks == 1 && more) { if (pf) asm volatile("s_waitcnt vmcnt(3)" ::: "memory"); else asm volatile("s_waitcnt vmcnt(0)" ::: "memory"); }
;             if (pf) { PIECE(s2, ks * 3 + 0); PIECE(s2, ks * 3 + 1); PIECE(s2, ks * 3 + 2); }
;             asm volatile("s_waitcnt lgkmcnt(0)" ::: "memory");
;             BAR();
;             __builtin_amdgcn_s_setprio(1);
; #pragma unroll
;             for (int mi = 0; mi < 4; ++mi)
; #pragma unroll
;                 for (int ni = 0; ni < 4; ++ni) acc[mi][ni] = __builtin_amdgcn_mfma_f32_16x16x32_bf16(bfr[ni], af[mi], acc[mi][ni], 0, 0, 0);
;             __builtin_amdgcn_s_setprio(0);
;             BAR();
;         }
;         st = st == 2 ? 0 : st + 1;
;     }
	s_sub_u32 s0, s0, 1
	s_cmp_lg_u32 s0, 0
	s_cbranch_scc1 .Lgu_kloop
	s_cmp_lg_u32 s54, 0
	s_cbranch_scc1 .Lgu_epi
	ds_read_b128 v[0:3], v188 offset:16
	ds_read_b128 v[4:7], v189 offset:16
	ds_read_b128 v[8:11], v188 offset:2064
	ds_read_b128 v[12:15], v189 offset:2064
	ds_read_b128 v[196:199], v188 offset:16400
	ds_read_b128 v[200:203], v189 offset:16400
	ds_read_b128 v[204:207], v188 offset:18448
	ds_read_b128 v[208:211], v189 offset:18448
	ds_read_b128 v[152:155], v186 offset:16
	ds_read_b128 v[156:159], v187 offset:16
	ds_read_b128 v[160:163], v186 offset:2064
	ds_read_b128 v[164:167], v187 offset:2064
	ds_read_b128 v[168:171], v186 offset:4112
	ds_read_b128 v[172:175], v187 offset:4112
	ds_read_b128 v[176:179], v186 offset:6160
	ds_read_b128 v[180:183], v187 offset:6160
	s_add_i32 m0, s39, 0xc000
	s_nop 0
	global_load_lds_dwordx4 v184, s[68:69]
	s_add_i32 m0, s39, 0xc400
	s_nop 0
	global_load_lds_dwordx4 v185, s[68:69]
	s_add_u32 s68, s68, 0x80
	s_addc_u32 s69, s69, 0
	s_waitcnt lgkmcnt(0)
	s_waitcnt vmcnt(8)
	s_barrier
	s_setprio 1
	v_mfma_f32_16x16x32_bf16 v[24:27], v[0:3], v[152:155], v[24:27]
	v_mfma_f32_16x16x32_bf16 v[28:31], v[8:11], v[152:155], v[28:31]
	v_mfma_f32_16x16x32_bf16 v[32:35], v[0:3], v[160:163], v[32:35]
	v_mfma_f32_16x16x32_bf16 v[36:39], v[8:11], v[160:163], v[36:39]
	v_mfma_f32_16x16x32_bf16 v[40:43], v[0:3], v[168:171], v[40:43]
	v_mfma_f32_16x16x32_bf16 v[44:47], v[8:11], v[168:171], v[44:47]
	v_mfma_f32_16x16x32_bf16 v[48:51], v[0:3], v[176:179], v[48:51]
	v_mfma_f32_16x16x32_bf16 v[52:55], v[8:11], v[176:179], v[52:55]
	v_mfma_f32_16x16x32_bf16 v[24:27], v[4:7], v[156:159], v[24:27]
	v_mfma_f32_16x16x32_bf16 v[28:31], v[12:15], v[156:159], v[28:31]
	v_mfma_f32_16x16x32_bf16 v[32:35], v[4:7], v[164:167], v[32:35]
	v_mfma_f32_16x16x32_bf16 v[36:39], v[12:15], v[164:167], v[36:39]
	v_mfma_f32_16x16x32_bf16 v[40:43], v[4:7], v[172:175], v[40:43]
	v_mfma_f32_16x16x32_bf16 v[44:47], v[12:15], v[172:175], v[44:47]
	v_mfma_f32_16x16x32_bf16 v[48:51], v[4:7], v[180:183], v[48:51]
	v_mfma_f32_16x16x32_bf16 v[52:55], v[12:15], v[180:183], v[52:55]
	v_mfma_f32_16x16x32_bf16 v[56:59], v[196:199], v[152:155], v[56:59]
	v_mfma_f32_16x16x32_bf16 v[60:63], v[204:207], v[152:155], v[60:63]
	v_mfma_f32_16x16x32_bf16 v[64:67], v[196:199], v[160:163], v[64:67]
	v_mfma_f32_16x16x32_bf16 v[68:71], v[204:207], v[160:163], v[68:71]
	v_mfma_f32_16x16x32_bf16 v[72:75], v[196:199], v[168:171], v[72:75]
	v_mfma_f32_16x16x32_bf16 v[76:79], v[204:207], v[168:171], v[76:79]
	v_mfma_f32_16x16x32_bf16 v[80:83], v[196:199], v[176:179], v[80:83]
	v_mfma_f32_16x16x32_bf16 v[84:87], v[204:207], v[176:179], v[84:87]
	v_mfma_f32_16x16x32_bf16 v[56:59], v[200:203], v[156:159], v[56:59]
	v_mfma_f32_16x16x32_bf16 v[60:63], v[208:211], v[156:159], v[60:63]
	v_mfma_f32_16x16x32_bf16 v[64:67], v[200:203], v[164:167], v[64:67]
	v_mfma_f32_16x16x32_bf16 v[68:71], v[208:211], v[164:167], v[68:71]
	v_mfma_f32_16x16x32_bf16 v[72:75], v[200:203], v[172:175], v[72:75]
	v_mfma_f32_16x16x32_bf16 v[76:79], v[208:211], v[172:175], v[76:79]
	v_mfma_f32_16x16x32_bf16 v[80:83], v[200:203], v[180:183], v[80:83]
	v_mfma_f32_16x16x32_bf16 v[84:87], v[208:211], v[180:183], v[84:87]
	s_setprio 0
	s_barrier
	ds_read_b128 v[152:155], v186 offset:16400
	ds_read_b128 v[156:159], v187 offset:16400
	ds_read_b128 v[160:163], v186 offset:18448
	ds_read_b128 v[164:167], v187 offset:18448
	ds_read_b128 v[168:171], v186 offset:20496
	ds_read_b128 v[172:175], v187 offset:20496
	ds_read_b128 v[176:179], v186 offset:22544
	ds_read_b128 v[180:183], v187 offset:22544
	s_waitcnt lgkmcnt(0)
	s_waitcnt vmcnt(2)
	s_barrier
	s_setprio 1
	v_mfma_f32_16x16x32_bf16 v[88:91], v[0:3], v[152:155], v[88:91]
	v_mfma_f32_16x16x32_bf16 v[92:95], v[8:11], v[152:155], v[92:95]
	v_mfma_f32_16x16x32_bf16 v[96:99], v[0:3], v[160:163], v[96:99]
	v_mfma_f32_16x16x32_bf16 v[100:103], v[8:11], v[160:163], v[100:103]
	v_mfma_f32_16x16x32_bf16 v[104:107], v[0:3], v[168:171], v[104:107]
	v_mfma_f32_16x16x32_bf16 v[108:111], v[8:11], v[168:171], v[108:111]
	v_mfma_f32_16x16x32_bf16 v[112:115], v[0:3], v[176:179], v[112:115]
	v_mfma_f32_16x16x32_bf16 v[116:119], v[8:11], v[176:179], v[116:119]
	v_mfma_f32_16x16x32_bf16 v[88:91], v[4:7], v[156:159], v[88:91]
	v_mfma_f32_16x16x32_bf16 v[92:95], v[12:15], v[156:159], v[92:95]
	v_mfma_f32_16x16x32_bf16 v[96:99], v[4:7], v[164:167], v[96:99]
	v_mfma_f32_16x16x32_bf16 v[100:103], v[12:15], v[164:167], v[100:103]
	v_mfma_f32_16x16x32_bf16 v[104:107], v[4:7], v[172:175], v[104:107]
	v_mfma_f32_16x16x32_bf16 v[108:111], v[12:15], v[172:175], v[108:111]
	v_mfma_f32_16x16x32_bf16 v[112:115], v[4:7], v[180:183], v[112:115]
	v_mfma_f32_16x16x32_bf16 v[116:119], v[12:15], v[180:183], v[116:119]
	v_mfma_f32_16x16x32_bf16 v[120:123], v[196:199], v[152:155], v[120:123]
	v_mfma_f32_16x16x32_bf16 v[124:127], v[204:207], v[152:155], v[124:127]
	v_mfma_f32_16x16x32_bf16 v[128:131], v[196:199], v[160:163], v[128:131]
	v_mfma_f32_16x16x32_bf16 v[132:135], v[204:207], v[160:163], v[132:135]
	v_mfma_f32_16x16x32_bf16 v[136:139], v[196:199], v[168:171], v[136:139]
	v_mfma_f32_16x16x32_bf16 v[140:143], v[204:207], v[168:171], v[140:143]
	v_mfma_f32_16x16x32_bf16 v[144:147], v[196:199], v[176:179], v[144:147]
	v_mfma_f32_16x16x32_bf16 v[148:151], v[204:207], v[176:179], v[148:151]
	v_mfma_f32_16x16x32_bf16 v[120:123], v[200:203], v[156:159], v[120:123]
	v_mfma_f32_16x16x32_bf16 v[124:127], v[208:211], v[156:159], v[124:127]
	v_mfma_f32_16x16x32_bf16 v[128:131], v[200:203], v[164:167], v[128:131]
	v_mfma_f32_16x16x32_bf16 v[132:135], v[208:211], v[164:167], v[132:135]
	v_mfma_f32_16x16x32_bf16 v[136:139], v[200:203], v[172:175], v[136:139]
	v_mfma_f32_16x16x32_bf16 v[140:143], v[208:211], v[172:175], v[140:143]
	v_mfma_f32_16x16x32_bf16 v[144:147], v[200:203], v[180:183], v[144:147]
	v_mfma_f32_16x16x32_bf16 v[148:151], v[208:211], v[180:183], v[148:151]
	s_setprio 0
	s_barrier
; #define LAS __attribute__((address_space(3)))
; #define BAR() { __builtin_amdgcn_sched_barrier(0); __builtin_amdgcn_s_barrier(); asm volatile("" ::: "memory"); __builtin_amdgcn_sched_barrier(0); }
; DI void gemm_stream2(const bf16_t* __restrict__ A, int lda, const bf16_t* __restrict__ Bt, int ldb, int K, int m0, int n0, ...
;     ...
;     for (int kt = 0; kt < nk; ++kt) {
;         const bool pf = (kt + 2 < nk) || has_next, more = (kt + 1 < nk) || has_next;
;         const bf16_t* pa = (kt + 2 < nk) ? ga + (kt + 2) * 64 : gan + (kt + 2 - nk) * 64;
;         const bf16_t* pb = (kt + 2 < nk) ? gb + (kt + 2) * 64 : gbn + (kt + 2 - nk) * 64;
;         const int plda = (kt + 2 < nk) ? lda : ldan, pldb = (kt + 2 < nk) ? ldb : ldbn;
;         const int s2 = st >= 1 ? st - 1 : 2;
;         const LAS char* base = lds + st * 49152;
; #pragma unroll
;         for (int ks = 0; ks < 2; ++ks) {
;             const unsigned fo = ks ? fo1 : fo0;
;             bf16x8 af[4], bfr[4];
; #pragma unroll
;             for (int i = 0; i < 4; ++i) { af[i] = *(const LAS bf16x8*)(base + aoff + i * 2048 + fo); bfr[i] = *(const LAS bf16x8*)(base + boff + i * 2048 + fo); }
;             if (ks == 1 && more) { if (pf) asm volatile("s_waitcnt vmcnt(3)" ::: "memory"); else asm volatile("s_waitcnt vmcnt(0)" ::: "memory"); }
;             if (pf) { PIECE(s2, ks * 3 + 0); PIECE(s2, ks * 3 + 1); PIECE(s2, ks * 3 + 2); }
;             asm volatile("s_waitcnt lgkmcnt(0)" ::: "memory");
;             BAR();
;             __builtin_amdgcn_s_setprio(1);
; #pragma unroll
;             for (int mi = 0; mi < 4; ++mi)
; #pragma unroll
;                 for (int ni = 0; ni < 4; ++ni) acc[mi][ni] = __builtin_amdgcn_mfma_f32_16x16x32_bf16(bfr[ni], af[mi], acc[mi][ni], 0, 0, 0);
;             __builtin_amdgcn_s_setprio(0);
;             BAR();
;         }
;         st = st == 2 ? 0 : st + 1;
;     }
;     if (grp == 0) BAR();
	ds_read_b128 v[0:3], v188 offset:32784
	ds_read_b128 v[4:7], v189 offset:32784
	ds_read_b128 v[8:11], v188 offset:34832
	ds_read_b128 v[12:15], v189 offset:34832
	ds_read_b128 v[196:199], v188 offset:49168
	ds_read_b128 v[200:203], v189 offset:49168
	ds_read_b128 v[204:207], v188 offset:51216
	ds_read_b128 v[208:211], v189 offset:51216
	ds_read_b128 v[152:155], v186 offset:32784
	ds_read_b128 v[156:159], v187 offset:32784
	ds_read_b128 v[160:163], v186 offset:34832
	ds_read_b128 v[164:167], v187 offset:34832
	ds_read_b128 v[168:171], v186 offset:36880
	ds_read_b128 v[172:175], v187 offset:36880
	ds_read_b128 v[176:179], v186 offset:38928
	ds_read_b128 v[180:183], v187 offset:38928
	s_waitcnt lgkmcnt(0)
	s_waitcnt vmcnt(0)
	s_barrier
	s_setprio 1
	v_mfma_f32_16x16x32_bf16 v[24:27], v[0:3], v[152:155], v[24:27]
	v_mfma_f32_16x16x32_bf16 v[28:31], v[8:11], v[152:155], v[28:31]
	v_mfma_f32_16x16x32_bf16 v[32:35], v[0:3], v[160:163], v[32:35]
	v_mfma_f32_16x16x32_bf16 v[36:39], v[8:11], v[160:163], v[36:39]
	v_mfma_f32_16x16x32_bf16 v[40:43], v[0:3], v[168:171], v[40:43]
	v_mfma_f32_16x16x32_bf16 v[44:47], v[8:11], v[168:171], v[44:47]
	v_mfma_f32_16x16x32_bf16 v[48:51], v[0:3], v[176:179], v[48:51]
	v_mfma_f32_16x16x32_bf16 v[52:55], v[8:11], v[176:179], v[52:55]
	v_mfma_f32_16x16x32_bf16 v[24:27], v[4:7], v[156:159], v[24:27]
	v_mfma_f32_16x16x32_bf16 v[28:31], v[12:15], v[156:159], v[28:31]
	v_mfma_f32_16x16x32_bf16 v[32:35], v[4:7], v[164:167], v[32:35]
	v_mfma_f32_16x16x32_bf16 v[36:39], v[12:15], v[164:167], v[36:39]
	v_mfma_f32_16x16x32_bf16 v[40:43], v[4:7], v[172:175], v[40:43]
	v_mfma_f32_16x16x32_bf16 v[44:47], v[12:15], v[172:175], v[44:47]
	v_mfma_f32_16x16x32_bf16 v[48:51], v[4:7], v[180:183], v[48:51]
	v_mfma_f32_16x16x32_bf16 v[52:55], v[12:15], v[180:183], v[52:55]
	v_mfma_f32_16x16x32_bf16 v[56:59], v[196:199], v[152:155], v[56:59]
	v_mfma_f32_16x16x32_bf16 v[60:63], v[204:207], v[152:155], v[60:63]
	v_mfma_f32_16x16x32_bf16 v[64:67], v[196:199], v[160:163], v[64:67]
	v_mfma_f32_16x16x32_bf16 v[68:71], v[204:207], v[160:163], v[68:71]
	v_mfma_f32_16x16x32_bf16 v[72:75], v[196:199], v[168:171], v[72:75]
	v_mfma_f32_16x16x32_bf16 v[76:79], v[204:207], v[168:171], v[76:79]
	v_mfma_f32_16x16x32_bf16 v[80:83], v[196:199], v[176:179], v[80:83]
	v_mfma_f32_16x16x32_bf16 v[84:87], v[204:207], v[176:179], v[84:87]
	v_mfma_f32_16x16x32_bf16 v[56:59], v[200:203], v[156:159], v[56:59]
	v_mfma_f32_16x16x32_bf16 v[60:63], v[208:211], v[156:159], v[60:63]
	v_mfma_f32_16x16x32_bf16 v[64:67], v[200:203], v[164:167], v[64:67]
	v_mfma_f32_16x16x32_bf16 v[68:71], v[208:211], v[164:167], v[68:71]
	v_mfma_f32_16x16x32_bf16 v[72:75], v[200:203], v[172:175], v[72:75]
	v_mfma_f32_16x16x32_bf16 v[76:79], v[208:211], v[172:175], v[76:79]
	v_mfma_f32_16x16x32_bf16 v[80:83], v[200:203], v[180:183], v[80:83]
	v_mfma_f32_16x16x32_bf16 v[84:87], v[208:211], v[180:183], v[84:87]
	s_setprio 0
	s_barrier
	ds_read_b128 v[152:155], v186 offset:49168
	ds_read_b128 v[156:159], v187 offset:49168
	ds_read_b128 v[160:163], v186 offset:51216
	ds_read_b128 v[164:167], v187 offset:51216
	ds_read_b128 v[168:171], v186 offset:53264
	ds_read_b128 v[172:175], v187 offset:53264
	ds_read_b128 v[176:179], v186 offset:55312
	ds_read_b128 v[180:183], v187 offset:55312
	s_waitcnt lgkmcnt(0)
	s_barrier
	s_setprio 1
	v_mfma_f32_16x16x32_bf16 v[88:91], v[0:3], v[152:155], v[88:91]
	v_mfma_f32_16x16x32_bf16 v[92:95], v[8:11], v[152:155], v[92:95]
	v_mfma_f32_16x16x32_bf16 v[96:99], v[0:3], v[160:163], v[96:99]
	v_mfma_f32_16x16x32_bf16 v[100:103], v[8:11], v[160:163], v[100:103]
	v_mfma_f32_16x16x32_bf16 v[104:107], v[0:3], v[168:171], v[104:107]
	v_mfma_f32_16x16x32_bf16 v[108:111], v[8:11], v[168:171], v[108:111]
	v_mfma_f32_16x16x32_bf16 v[112:115], v[0:3], v[176:179], v[112:115]
	v_mfma_f32_16x16x32_bf16 v[116:119], v[8:11], v[176:179], v[116:119]
	v_mfma_f32_16x16x32_bf16 v[88:91], v[4:7], v[156:159], v[88:91]
	v_mfma_f32_16x16x32_bf16 v[92:95], v[12:15], v[156:159], v[92:95]
	v_mfma_f32_16x16x32_bf16 v[96:99], v[4:7], v[164:167], v[96:99]
	v_mfma_f32_16x16x32_bf16 v[100:103], v[12:15], v[164:167], v[100:103]
	v_mfma_f32_16x16x32_bf16 v[104:107], v[4:7], v[172:175], v[104:107]
	v_mfma_f32_16x16x32_bf16 v[108:111], v[12:15], v[172:175], v[108:111]
	v_mfma_f32_16x16x32_bf16 v[112:115], v[4:7], v[180:183], v[112:115]
	v_mfma_f32_16x16x32_bf16 v[116:119], v[12:15], v[180:183], v[116:119]
	v_mfma_f32_16x16x32_bf16 v[120:123], v[196:199], v[152:155], v[120:123]
	v_mfma_f32_16x16x32_bf16 v[124:127], v[204:207], v[152:155], v[124:127]
	v_mfma_f32_16x16x32_bf16 v[128:131], v[196:199], v[160:163], v[128:131]
	v_mfma_f32_16x16x32_bf16 v[132:135], v[204:207], v[160:163], v[132:135]
	v_mfma_f32_16x16x32_bf16 v[136:139], v[196:199], v[168:171], v[136:139]
	v_mfma_f32_16x16x32_bf16 v[140:143], v[204:207], v[168:171], v[140:143]
	v_mfma_f32_16x16x32_bf16 v[144:147], v[196:199], v[176:179], v[144:147]
	v_mfma_f32_16x16x32_bf16 v[148:151], v[204:207], v[176:179], v[148:151]
	v_mfma_f32_16x16x32_bf16 v[120:123], v[200:203], v[156:159], v[120:123]
	v_mfma_f32_16x16x32_bf16 v[124:127], v[208:211], v[156:159], v[124:127]
	v_mfma_f32_16x16x32_bf16 v[128:131], v[200:203], v[164:167], v[128:131]
	v_mfma_f32_16x16x32_bf16 v[132:135], v[208:211], v[164:167], v[132:135]
	v_mfma_f32_16x16x32_bf16 v[136:139], v[200:203], v[172:175], v[136:139]
	v_mfma_f32_16x16x32_bf16 v[140:143], v[208:211], v[172:175], v[140:143]
	v_mfma_f32_16x16x32_bf16 v[144:147], v[200:203], v[180:183], v[144:147]
	v_mfma_f32_16x16x32_bf16 v[148:151], v[208:211], v[180:183], v[148:151]
	s_setprio 0
	s_barrier
	s_cmp_lg_u32 s33, 0
	s_cbranch_scc1 .Lgu_epi
	s_barrier

; #define BAR() { __builtin_amdgcn_sched_barrier(0); __builtin_amdgcn_s_barrier(); asm volatile("" ::: "memory"); __builtin_amdgcn_sched_barrier(0); }
; DI void gemm_stream2(const bf16_t* __restrict__ A, int lda, const bf16_t* __restrict__ Bt, int ldb, int K, int m0, int n0, ...
;     ...
;     const int wave = __builtin_amdgcn_readfirstlane(tid >> 6), lane = tid & 63, wm = wave >> 1, wn = wave & 1, r = lane & 15, q = lane >> 4;
;     const int sc0 = ((lane & 7) ^ (lane >> 4)) * 8, sc1 = ((lane & 7) ^ (4 | (lane >> 4))) * 8;
;     const bf16_t* ga = A + (size_t)(m0 + wave * 32 + (lane >> 3)) * lda;
;     const bf16_t* gb = Bt + (size_t)(n0 + wave * 16 + (lane >> 3)) * ldb;
;     const bf16_t* gan = An + (size_t)(m0n + wave * 32 + (lane >> 3)) * ldan;
;     const bf16_t* gbn = Btn + (size_t)(n0n + wave * 16 + (lane >> 3)) * ldbn;
;     const unsigned wa = (unsigned)wave * 4096u, wbb = 32768u + (unsigned)wave * 2048u;
;     ...
;     const int sw = r >> 1;
;     const unsigned fo0 = (unsigned)(r * 128 + ((q ^ sw) << 4)), fo1 = (unsigned)(r * 128 + (((q ^ sw) ^ 4) << 4));
;     const unsigned aoff = (unsigned)(wm * 64) * 128u, boff = 32768u + (unsigned)(wn * 64) * 128u;
;     const int nk = K / 64;
;     const int grp = wave >> 2;
;     ...
;     int st = rg.st;
;     if (!rg.primed) {
;         const int s1p = st == 2 ? 0 : st + 1;
;         BAR();
;         STAGE(st, 0);
;         STAGE(s1p, 1);
;         asm volatile("s_waitcnt vmcnt(6)" ::: "memory");
;         BAR();
;     }
;     if (grp == 1) BAR();
; DI void gemm_y(const Params& p, const bf16_t* A, int lda, size_t woff, int K, int kper, int bid, int nb, char* smem, const int tid) {
;     ...
;     for (; have; tm = tm2, tn = tn2) {
;         have = ti.next(tm2, tn2);
;         const int m0 = tm * 256, n0 = tn * 128;
;         f32x4 acc[4][4]; zero_acc(acc);
;         gemm_stream(A, lda, Bt, K, K, m0, n0, have, tm2 * 256, tn2 * 128, smem, acc, tid, rg);
.Lgyd_lanes:
	v_and_b32_e32 v190, 63, v193
	v_and_b32_e32 v191, 15, v190
	v_lshrrev_b32_e32 v17, 4, v190
	v_lshrrev_b32_e32 v18, 3, v190
	v_and_b32_e32 v19, 7, v190
	v_xor_b32_e32 v195, v19, v17
	v_lshlrev_b32_e32 v195, 4, v195
	s_mov_b32 s1, 0x1600
	v_mad_u32_u24 v184, v18, s1, v195
	v_or_b32_e32 v195, 4, v17
	v_xor_b32_e32 v195, v19, v195
	v_lshlrev_b32_e32 v195, 4, v195
	v_add_u32_e32 v227, 8, v18
	v_mad_u32_u24 v185, v227, s1, v195
	v_lshrrev_b32_e32 v195, 1, v191
	v_xor_b32_e32 v195, v17, v195
	v_lshlrev_b32_e32 v195, 4, v195
	s_lshl_b32 s1, s33, 6
	v_add_u32_e32 v227, s1, v191
	v_lshl_add_u32 v186, v227, 7, v195
	v_xor_b32_e32 v187, 64, v186
	v_lshlrev_b32_e32 v228, 11, v227
	s_lshl_b32 s1, s36, 5
	v_add_u32_e32 v227, s1, v191
	v_lshl_add_u32 v188, v227, 7, v195
	v_add_u32_e32 v188, 0x10000, v188
	v_xor_b32_e32 v189, 64, v188
	s_lshl_b32 s1, s36, 6
	v_lshl_add_u32 v229, v17, 3, s1
	v_add_u32_e32 v237, v228, v229
	s_add_i32 m0, s39, 0x10000
	s_nop 0
	global_load_lds_dwordx4 v184, s[70:71]
	s_add_i32 m0, s39, 0x10400
	s_nop 0
	global_load_lds_dwordx4 v185, s[70:71]
	s_add_u32 s70, s70, 0x80
	s_addc_u32 s71, s71, 0
	s_add_i32 m0, s39, 0x0
	s_nop 0
	global_load_lds_dwordx4 v184, s[66:67]
	s_add_i32 m0, s39, 0x400
	s_nop 0
	global_load_lds_dwordx4 v185, s[66:67]
	s_add_u32 s66, s66, 0x80
	s_addc_u32 s67, s67, 0
	s_add_i32 m0, s39, 0x14000
	s_nop 0
	global_load_lds_dwordx4 v184, s[72:73]
	s_add_i32 m0, s39, 0x14400
	s_nop 0
	global_load_lds_dwordx4 v185, s[72:73]
	s_add_u32 s72, s72, 0x80
	s_addc_u32 s73, s73, 0
	s_add_i32 m0, s39, 0x4000
	s_nop 0
	global_load_lds_dwordx4 v184, s[68:69]
	s_add_i32 m0, s39, 0x4400
	s_nop 0
	global_load_lds_dwordx4 v185, s[68:69]
	s_add_u32 s68, s68, 0x80
	s_addc_u32 s69, s69, 0
	s_add_i32 m0, s39, 0x18000
	s_nop 0
	global_load_lds_dwordx4 v184, s[70:71]
	s_add_i32 m0, s39, 0x18400
	s_nop 0
	global_load_lds_dwordx4 v185, s[70:71]
	s_add_u32 s70, s70, 0x80
	s_addc_u32 s71, s71, 0
	s_add_i32 m0, s39, 0x8000
	s_nop 0
	global_load_lds_dwordx4 v184, s[66:67]
	s_add_i32 m0, s39, 0x8400
	s_nop 0
	global_load_lds_dwordx4 v185, s[66:67]
	s_add_u32 s66, s66, 0x80
	s_addc_u32 s67, s67, 0
	s_add_i32 m0, s39, 0x1c000
	s_nop 0
	global_load_lds_dwordx4 v184, s[72:73]
	s_add_i32 m0, s39, 0x1c400
	s_nop 0
	global_load_lds_dwordx4 v185, s[72:73]
	s_add_u32 s72, s72, 0x80
	s_addc_u32 s73, s73, 0
	s_waitcnt vmcnt(8)
	s_barrier
	s_cmp_eq_u32 s33, 0
	s_cbranch_scc1 .Lgyd_lead
	s_barrier
.Lgyd_lead:
.Lgyd_item:
	s_cmp_eq_u32 s55, 0
	s_cbranch_scc0 .Lgyd_nx_unit
	s_add_u32 s76, s51, s53
	s_cmp_lt_u32 s76, s52
	s_cbranch_scc0 .Lgyd_nx_first_unit
	s_mov_b32 s54, 1
	s_mov_b32 s93, 0
	s_lshr_b32 s1, s76, 5
	s_and_b32 s2, s76, 31
	s_lshr_b32 s60, s2, 3
	s_and_b32 s2, s2, 7
	s_lshl_b32 s1, s1, 3
	s_add_i32 s59, s1, s2
	s_mul_i32 s2, s10, 0x16000
	s_mul_i32 s1, s59, 0x160000
	s_add_u32 s1, s1, s2
	s_add_u32 s74, s88, s1
	s_addc_u32 s75, s89, 0
	s_add_u32 s74, s74, 0x52c0000
	s_addc_u32 s75, s75, 0
	s_add_u32 s78, s74, 0xb0000
	s_addc_u32 s79, s75, 0
	s_mul_i32 s1, s60, 0x160000
	s_add_u32 s1, s1, s2
	s_add_u32 s1, s1, s61
	s_add_u32 s80, s88, s1
	s_addc_u32 s81, s89, 0
	s_add_u32 s82, s80, 0xb0000
	s_addc_u32 s83, s81, 0
	s_branch .Lgyd_nx_done

; #define LAS __attribute__((address_space(3)))
; #define BAR() { __builtin_amdgcn_sched_barrier(0); __builtin_amdgcn_s_barrier(); asm volatile("" ::: "memory"); __builtin_amdgcn_sched_barrier(0); }
; DI void gemm_stream2(const bf16_t* __restrict__ A, int lda, const bf16_t* __restrict__ Bt, int ldb, int K, int m0, int n0, ...
;     ...
;         for (int ks = 0; ks < 2; ++ks) {
;             const unsigned fo = ks ? fo1 : fo0;
;             bf16x8 af[4], bfr[4];
; #pragma unroll
;             for (int i = 0; i < 4; ++i) { af[i] = *(const LAS bf16x8*)(base + aoff + i * 2048 + fo); bfr[i] = *(const LAS bf16x8*)(base + boff + i * 2048 + fo); }
;             if (ks == 1 && more) { if (pf) asm volatile("s_waitcnt vmcnt(3)" ::: "memory"); else asm volatile("s_waitcnt vmcnt(0)" ::: "memory"); }
;             if (pf) { PIECE(s2, ks * 3 + 0); PIECE(s2, ks * 3 + 1); PIECE(s2, ks * 3 + 2); }
;             asm volatile("s_waitcnt lgkmcnt(0)" ::: "memory");
;             BAR();
;             __builtin_amdgcn_s_setprio(1);
; #pragma unroll
;             for (int mi = 0; mi < 4; ++mi)
; #pragma unroll
;                 for (int ni = 0; ni < 4; ++ni) acc[mi][ni] = __builtin_amdgcn_mfma_f32_16x16x32_bf16(bfr[ni], af[mi], acc[mi][ni], 0, 0, 0);
;             __builtin_amdgcn_s_setprio(0);
;             BAR();
;         }
.Lgyd_nosw2:
	s_add_i32 m0, s39, 0x4000
	s_nop 0
	global_load_lds_dwordx4 v184, s[68:69]
	s_add_i32 m0, s39, 0x4400
	s_nop 0
	global_load_lds_dwordx4 v185, s[68:69]
	s_add_u32 s68, s68, 0x80
	s_addc_u32 s69, s69, 0
	s_waitcnt lgkmcnt(0)
	s_waitcnt vmcnt(8)
	s_barrier
	s_setprio 1
	v_mfma_f32_16x16x32_bf16 v[24:27], v[0:3], v[152:155], v[24:27]
	v_mfma_f32_16x16x32_bf16 v[28:31], v[8:11], v[152:155], v[28:31]
	v_mfma_f32_16x16x32_bf16 v[32:35], v[0:3], v[160:163], v[32:35]
	v_mfma_f32_16x16x32_bf16 v[36:39], v[8:11], v[160:163], v[36:39]
	v_mfma_f32_16x16x32_bf16 v[40:43], v[0:3], v[168:171], v[40:43]
	v_mfma_f32_16x16x32_bf16 v[44:47], v[8:11], v[168:171], v[44:47]
	v_mfma_f32_16x16x32_bf16 v[48:51], v[0:3], v[176:179], v[48:51]
	v_mfma_f32_16x16x32_bf16 v[52:55], v[8:11], v[176:179], v[52:55]
	v_mfma_f32_16x16x32_bf16 v[24:27], v[4:7], v[156:159], v[24:27]
	v_mfma_f32_16x16x32_bf16 v[28:31], v[12:15], v[156:159], v[28:31]
	v_mfma_f32_16x16x32_bf16 v[32:35], v[4:7], v[164:167], v[32:35]
	v_mfma_f32_16x16x32_bf16 v[36:39], v[12:15], v[164:167], v[36:39]
	v_mfma_f32_16x16x32_bf16 v[40:43], v[4:7], v[172:175], v[40:43]
	v_mfma_f32_16x16x32_bf16 v[44:47], v[12:15], v[172:175], v[44:47]
	v_mfma_f32_16x16x32_bf16 v[48:51], v[4:7], v[180:183], v[48:51]
	v_mfma_f32_16x16x32_bf16 v[52:55], v[12:15], v[180:183], v[52:55]
	v_mfma_f32_16x16x32_bf16 v[56:59], v[196:199], v[152:155], v[56:59]
	v_mfma_f32_16x16x32_bf16 v[60:63], v[204:207], v[152:155], v[60:63]
	v_mfma_f32_16x16x32_bf16 v[64:67], v[196:199], v[160:163], v[64:67]
	v_mfma_f32_16x16x32_bf16 v[68:71], v[204:207], v[160:163], v[68:71]
	v_mfma_f32_16x16x32_bf16 v[72:75], v[196:199], v[168:171], v[72:75]
	v_mfma_f32_16x16x32_bf16 v[76:79], v[204:207], v[168:171], v[76:79]
	v_mfma_f32_16x16x32_bf16 v[80:83], v[196:199], v[176:179], v[80:83]
	v_mfma_f32_16x16x32_bf16 v[84:87], v[204:207], v[176:179], v[84:87]
	v_mfma_f32_16x16x32_bf16 v[56:59], v[200:203], v[156:159], v[56:59]
	v_mfma_f32_16x16x32_bf16 v[60:63], v[208:211], v[156:159], v[60:63]
	v_mfma_f32_16x16x32_bf16 v[64:67], v[200:203], v[164:167], v[64:67]
	v_mfma_f32_16x16x32_bf16 v[68:71], v[208:211], v[164:167], v[68:71]
	v_mfma_f32_16x16x32_bf16 v[72:75], v[200:203], v[172:175], v[72:75]
	v_mfma_f32_16x16x32_bf16 v[76:79], v[208:211], v[172:175], v[76:79]
	v_mfma_f32_16x16x32_bf16 v[80:83], v[200:203], v[180:183], v[80:83]
	v_mfma_f32_16x16x32_bf16 v[84:87], v[208:211], v[180:183], v[84:87]
	s_setprio 0
	s_barrier
	ds_read_b128 v[152:155], v186 offset:49168
	ds_read_b128 v[156:159], v187 offset:49168
	ds_read_b128 v[160:163], v186 offset:51216
	ds_read_b128 v[164:167], v187 offset:51216
	ds_read_b128 v[168:171], v186 offset:53264
	ds_read_b128 v[172:175], v187 offset:53264
	ds_read_b128 v[176:179], v186 offset:55312
	ds_read_b128 v[180:183], v187 offset:55312
	s_add_i32 m0, s39, 0x18000
	s_nop 0
	global_load_lds_dwordx4 v184, s[70:71]
	s_add_i32 m0, s39, 0x18400
	s_nop 0
	global_load_lds_dwordx4 v185, s[70:71]
	s_add_u32 s70, s70, 0x80
	s_addc_u32 s71, s71, 0
	s_add_i32 m0, s39, 0x8000
	s_nop 0
	global_load_lds_dwordx4 v184, s[66:67]
	s_add_i32 m0, s39, 0x8400
	s_nop 0
	global_load_lds_dwordx4 v185, s[66:67]
	s_add_u32 s66, s66, 0x80
	s_addc_u32 s67, s67, 0
	s_add_i32 m0, s39, 0x1c000
	s_nop 0
	global_load_lds_dwordx4 v184, s[72:73]
	s_add_i32 m0, s39, 0x1c400
	s_nop 0
	global_load_lds_dwordx4 v185, s[72:73]
	s_add_u32 s72, s72, 0x80
	s_addc_u32 s73, s73, 0
	s_waitcnt lgkmcnt(0)
	s_waitcnt vmcnt(8)
	s_barrier
	s_setprio 1
	v_mfma_f32_16x16x32_bf16 v[88:91], v[0:3], v[152:155], v[88:91]
	v_mfma_f32_16x16x32_bf16 v[92:95], v[8:11], v[152:155], v[92:95]
	v_mfma_f32_16x16x32_bf16 v[96:99], v[0:3], v[160:163], v[96:99]
	v_mfma_f32_16x16x32_bf16 v[100:103], v[8:11], v[160:163], v[100:103]
	v_mfma_f32_16x16x32_bf16 v[104:107], v[0:3], v[168:171], v[104:107]
	v_mfma_f32_16x16x32_bf16 v[108:111], v[8:11], v[168:171], v[108:111]
	v_mfma_f32_16x16x32_bf16 v[112:115], v[0:3], v[176:179], v[112:115]
	v_mfma_f32_16x16x32_bf16 v[116:119], v[8:11], v[176:179], v[116:119]
	v_mfma_f32_16x16x32_bf16 v[88:91], v[4:7], v[156:159], v[88:91]
	v_mfma_f32_16x16x32_bf16 v[92:95], v[12:15], v[156:159], v[92:95]
	v_mfma_f32_16x16x32_bf16 v[96:99], v[4:7], v[164:167], v[96:99]
	v_mfma_f32_16x16x32_bf16 v[100:103], v[12:15], v[164:167], v[100:103]
	v_mfma_f32_16x16x32_bf16 v[104:107], v[4:7], v[172:175], v[104:107]
	v_mfma_f32_16x16x32_bf16 v[108:111], v[12:15], v[172:175], v[108:111]
	v_mfma_f32_16x16x32_bf16 v[112:115], v[4:7], v[180:183], v[112:115]
	v_mfma_f32_16x16x32_bf16 v[116:119], v[12:15], v[180:183], v[116:119]
	v_mfma_f32_16x16x32_bf16 v[120:123], v[196:199], v[152:155], v[120:123]
	v_mfma_f32_16x16x32_bf16 v[124:127], v[204:207], v[152:155], v[124:127]
	v_mfma_f32_16x16x32_bf16 v[128:131], v[196:199], v[160:163], v[128:131]
	v_mfma_f32_16x16x32_bf16 v[132:135], v[204:207], v[160:163], v[132:135]
	v_mfma_f32_16x16x32_bf16 v[136:139], v[196:199], v[168:171], v[136:139]
	v_mfma_f32_16x16x32_bf16 v[140:143], v[204:207], v[168:171], v[140:143]
	v_mfma_f32_16x16x32_bf16 v[144:147], v[196:199], v[176:179], v[144:147]
	v_mfma_f32_16x16x32_bf16 v[148:151], v[204:207], v[176:179], v[148:151]
	v_mfma_f32_16x16x32_bf16 v[120:123], v[200:203], v[156:159], v[120:123]
	v_mfma_f32_16x16x32_bf16 v[124:127], v[208:211], v[156:159], v[124:127]
	v_mfma_f32_16x16x32_bf16 v[128:131], v[200:203], v[164:167], v[128:131]
	v_mfma_f32_16x16x32_bf16 v[132:135], v[208:211], v[164:167], v[132:135]
	v_mfma_f32_16x16x32_bf16 v[136:139], v[200:203], v[172:175], v[136:139]
	v_mfma_f32_16x16x32_bf16 v[140:143], v[208:211], v[172:175], v[140:143]
	v_mfma_f32_16x16x32_bf16 v[144:147], v[200:203], v[180:183], v[144:147]
	v_mfma_f32_16x16x32_bf16 v[148:151], v[208:211], v[180:183], v[148:151]
	s_setprio 0
	s_barrier
	s_sub_u32 s0, s0, 1
	s_cmp_lg_u32 s0, 0
	s_cbranch_scc1 .Lgyd_kloop
; #define LAS __attribute__((address_space(3)))
; #define BAR() { __builtin_amdgcn_sched_barrier(0); __builtin_amdgcn_s_barrier(); asm volatile("" ::: "memory"); __builtin_amdgcn_sched_barrier(0); }
; DI void gemm_stream2(const bf16_t* __restrict__ A, int lda, const bf16_t* __restrict__ Bt, int ldb, int K, int m0, int n0, ...
;     ...
;     for (int kt = 0; kt < nk; ++kt) {
;         const bool pf = (kt + 2 < nk) || has_next, more = (kt + 1 < nk) || has_next;
;         const bf16_t* pa = (kt + 2 < nk) ? ga + (kt + 2) * 64 : gan + (kt + 2 - nk) * 64;
;         const bf16_t* pb = (kt + 2 < nk) ? gb + (kt + 2) * 64 : gbn + (kt + 2 - nk) * 64;
;         const int plda = (kt + 2 < nk) ? lda : ldan, pldb = (kt + 2 < nk) ? ldb : ldbn;
;         const int s2 = st >= 1 ? st - 1 : 2;
;         const LAS char* base = lds + st * 49152;
; #pragma unroll
;         for (int ks = 0; ks < 2; ++ks) {
;             const unsigned fo = ks ? fo1 : fo0;
;             bf16x8 af[4], bfr[4];
; #pragma unroll
;             for (int i = 0; i < 4; ++i) { af[i] = *(const LAS bf16x8*)(base + aoff + i * 2048 + fo); bfr[i] = *(const LAS bf16x8*)(base + boff + i * 2048 + fo); }
;             if (ks == 1 && more) { if (pf) asm volatile("s_waitcnt vmcnt(3)" ::: "memory"); else asm volatile("s_waitcnt vmcnt(0)" ::: "memory"); }
;             if (pf) { PIECE(s2, ks * 3 + 0); PIECE(s2, ks * 3 + 1); PIECE(s2, ks * 3 + 2); }
;             asm volatile("s_waitcnt lgkmcnt(0)" ::: "memory");
;             BAR();
;             __builtin_amdgcn_s_setprio(1);
; #pragma unroll
;             for (int mi = 0; mi < 4; ++mi)
; #pragma unroll
;                 for (int ni = 0; ni < 4; ++ni) acc[mi][ni] = __builtin_amdgcn_mfma_f32_16x16x32_bf16(bfr[ni], af[mi], acc[mi][ni], 0, 0, 0);
;             __builtin_amdgcn_s_setprio(0);
;             BAR();
;         }
;         st = st == 2 ? 0 : st + 1;
;     }
.Lgyd_kdone:
	s_cmp_lg_u32 s54, 0
	s_cbranch_scc1 .Lgyd_epi
	ds_read_b128 v[0:3], v188 offset:16
	ds_read_b128 v[4:7], v189 offset:16
	ds_read_b128 v[8:11], v188 offset:2064
	ds_read_b128 v[12:15], v189 offset:2064
	ds_read_b128 v[196:199], v188 offset:16400
	ds_read_b128 v[200:203], v189 offset:16400
	ds_read_b128 v[204:207], v188 offset:18448
	ds_read_b128 v[208:211], v189 offset:18448
	ds_read_b128 v[152:155], v186 offset:16
	ds_read_b128 v[156:159], v187 offset:16
	ds_read_b128 v[160:163], v186 offset:2064
	ds_read_b128 v[164:167], v187 offset:2064
	ds_read_b128 v[168:171], v186 offset:4112
	ds_read_b128 v[172:175], v187 offset:4112
	ds_read_b128 v[176:179], v186 offset:6160
	ds_read_b128 v[180:183], v187 offset:6160
	s_add_i32 m0, s39, 0xc000
	s_nop 0
	global_load_lds_dwordx4 v184, s[68:69]
	s_add_i32 m0, s39, 0xc400
	s_nop 0
	global_load_lds_dwordx4 v185, s[68:69]
	s_add_u32 s68, s68, 0x80
	s_addc_u32 s69, s69, 0
	s_waitcnt lgkmcnt(0)
	s_waitcnt vmcnt(8)
	s_barrier
	s_setprio 1
	v_mfma_f32_16x16x32_bf16 v[24:27], v[0:3], v[152:155], v[24:27]
	v_mfma_f32_16x16x32_bf16 v[28:31], v[8:11], v[152:155], v[28:31]
	v_mfma_f32_16x16x32_bf16 v[32:35], v[0:3], v[160:163], v[32:35]
	v_mfma_f32_16x16x32_bf16 v[36:39], v[8:11], v[160:163], v[36:39]
	v_mfma_f32_16x16x32_bf16 v[40:43], v[0:3], v[168:171], v[40:43]
	v_mfma_f32_16x16x32_bf16 v[44:47], v[8:11], v[168:171], v[44:47]
	v_mfma_f32_16x16x32_bf16 v[48:51], v[0:3], v[176:179], v[48:51]
	v_mfma_f32_16x16x32_bf16 v[52:55], v[8:11], v[176:179], v[52:55]
	v_mfma_f32_16x16x32_bf16 v[24:27], v[4:7], v[156:159], v[24:27]
	v_mfma_f32_16x16x32_bf16 v[28:31], v[12:15], v[156:159], v[28:31]
	v_mfma_f32_16x16x32_bf16 v[32:35], v[4:7], v[164:167], v[32:35]
	v_mfma_f32_16x16x32_bf16 v[36:39], v[12:15], v[164:167], v[36:39]
	v_mfma_f32_16x16x32_bf16 v[40:43], v[4:7], v[172:175], v[40:43]
	v_mfma_f32_16x16x32_bf16 v[44:47], v[12:15], v[172:175], v[44:47]
	v_mfma_f32_16x16x32_bf16 v[48:51], v[4:7], v[180:183], v[48:51]
	v_mfma_f32_16x16x32_bf16 v[52:55], v[12:15], v[180:183], v[52:55]
	v_mfma_f32_16x16x32_bf16 v[56:59], v[196:199], v[152:155], v[56:59]
	v_mfma_f32_16x16x32_bf16 v[60:63], v[204:207], v[152:155], v[60:63]
	v_mfma_f32_16x16x32_bf16 v[64:67], v[196:199], v[160:163], v[64:67]
	v_mfma_f32_16x16x32_bf16 v[68:71], v[204:207], v[160:163], v[68:71]
	v_mfma_f32_16x16x32_bf16 v[72:75], v[196:199], v[168:171], v[72:75]
	v_mfma_f32_16x16x32_bf16 v[76:79], v[204:207], v[168:171], v[76:79]
	v_mfma_f32_16x16x32_bf16 v[80:83], v[196:199], v[176:179], v[80:83]
	v_mfma_f32_16x16x32_bf16 v[84:87], v[204:207], v[176:179], v[84:87]
	v_mfma_f32_16x16x32_bf16 v[56:59], v[200:203], v[156:159], v[56:59]
	v_mfma_f32_16x16x32_bf16 v[60:63], v[208:211], v[156:159], v[60:63]
	v_mfma_f32_16x16x32_bf16 v[64:67], v[200:203], v[164:167], v[64:67]
	v_mfma_f32_16x16x32_bf16 v[68:71], v[208:211], v[164:167], v[68:71]
	v_mfma_f32_16x16x32_bf16 v[72:75], v[200:203], v[172:175], v[72:75]
	v_mfma_f32_16x16x32_bf16 v[76:79], v[208:211], v[172:175], v[76:79]
	v_mfma_f32_16x16x32_bf16 v[80:83], v[200:203], v[180:183], v[80:83]
	v_mfma_f32_16x16x32_bf16 v[84:87], v[208:211], v[180:183], v[84:87]
	s_setprio 0
	s_barrier
	ds_read_b128 v[152:155], v186 offset:16400
	ds_read_b128 v[156:159], v187 offset:16400
	ds_read_b128 v[160:163], v186 offset:18448
	ds_read_b128 v[164:167], v187 offset:18448
	ds_read_b128 v[168:171], v186 offset:20496
	ds_read_b128 v[172:175], v187 offset:20496
	ds_read_b128 v[176:179], v186 offset:22544
	ds_read_b128 v[180:183], v187 offset:22544
	s_waitcnt lgkmcnt(0)
	s_waitcnt vmcnt(2)
	s_barrier
	s_setprio 1
	v_mfma_f32_16x16x32_bf16 v[88:91], v[0:3], v[152:155], v[88:91]
	v_mfma_f32_16x16x32_bf16 v[92:95], v[8:11], v[152:155], v[92:95]
	v_mfma_f32_16x16x32_bf16 v[96:99], v[0:3], v[160:163], v[96:99]
	v_mfma_f32_16x16x32_bf16 v[100:103], v[8:11], v[160:163], v[100:103]
	v_mfma_f32_16x16x32_bf16 v[104:107], v[0:3], v[168:171], v[104:107]
	v_mfma_f32_16x16x32_bf16 v[108:111], v[8:11], v[168:171], v[108:111]
	v_mfma_f32_16x16x32_bf16 v[112:115], v[0:3], v[176:179], v[112:115]
	v_mfma_f32_16x16x32_bf16 v[116:119], v[8:11], v[176:179], v[116:119]
	v_mfma_f32_16x16x32_bf16 v[88:91], v[4:7], v[156:159], v[88:91]
	v_mfma_f32_16x16x32_bf16 v[92:95], v[12:15], v[156:159], v[92:95]
	v_mfma_f32_16x16x32_bf16 v[96:99], v[4:7], v[164:167], v[96:99]
	v_mfma_f32_16x16x32_bf16 v[100:103], v[12:15], v[164:167], v[100:103]
	v_mfma_f32_16x16x32_bf16 v[104:107], v[4:7], v[172:175], v[104:107]
	v_mfma_f32_16x16x32_bf16 v[108:111], v[12:15], v[172:175], v[108:111]
	v_mfma_f32_16x16x32_bf16 v[112:115], v[4:7], v[180:183], v[112:115]
	v_mfma_f32_16x16x32_bf16 v[116:119], v[12:15], v[180:183], v[116:119]
	v_mfma_f32_16x16x32_bf16 v[120:123], v[196:199], v[152:155], v[120:123]
	v_mfma_f32_16x16x32_bf16 v[124:127], v[204:207], v[152:155], v[124:127]
	v_mfma_f32_16x16x32_bf16 v[128:131], v[196:199], v[160:163], v[128:131]
	v_mfma_f32_16x16x32_bf16 v[132:135], v[204:207], v[160:163], v[132:135]
	v_mfma_f32_16x16x32_bf16 v[136:139], v[196:199], v[168:171], v[136:139]
	v_mfma_f32_16x16x32_bf16 v[140:143], v[204:207], v[168:171], v[140:143]
	v_mfma_f32_16x16x32_bf16 v[144:147], v[196:199], v[176:179], v[144:147]
	v_mfma_f32_16x16x32_bf16 v[148:151], v[204:207], v[176:179], v[148:151]
	v_mfma_f32_16x16x32_bf16 v[120:123], v[200:203], v[156:159], v[120:123]
	v_mfma_f32_16x16x32_bf16 v[124:127], v[208:211], v[156:159], v[124:127]
	v_mfma_f32_16x16x32_bf16 v[128:131], v[200:203], v[164:167], v[128:131]
	v_mfma_f32_16x16x32_bf16 v[132:135], v[208:211], v[164:167], v[132:135]
	v_mfma_f32_16x16x32_bf16 v[136:139], v[200:203], v[172:175], v[136:139]
	v_mfma_f32_16x16x32_bf16 v[140:143], v[208:211], v[172:175], v[140:143]
	v_mfma_f32_16x16x32_bf16 v[144:147], v[200:203], v[180:183], v[144:147]
	v_mfma_f32_16x16x32_bf16 v[148:151], v[208:211], v[180:183], v[148:151]
	s_setprio 0
	s_barrier
; #define LAS __attribute__((address_space(3)))
; #define BAR() { __builtin_amdgcn_sched_barrier(0); __builtin_amdgcn_s_barrier(); asm volatile("" ::: "memory"); __builtin_amdgcn_sched_barrier(0); }
; DI void gemm_stream2(const bf16_t* __restrict__ A, int lda, const bf16_t* __restrict__ Bt, int ldb, int K, int m0, int n0, ...
;     ...
;     for (int kt = 0; kt < nk; ++kt) {
;         const bool pf = (kt + 2 < nk) || has_next, more = (kt + 1 < nk) || has_next;
;         const bf16_t* pa = (kt + 2 < nk) ? ga + (kt + 2) * 64 : gan + (kt + 2 - nk) * 64;
;         const bf16_t* pb = (kt + 2 < nk) ? gb + (kt + 2) * 64 : gbn + (kt + 2 - nk) * 64;
;         const int plda = (kt + 2 < nk) ? lda : ldan, pldb = (kt + 2 < nk) ? ldb : ldbn;
;         const int s2 = st >= 1 ? st - 1 : 2;
;         const LAS char* base = lds + st * 49152;
; #pragma unroll
;         for (int ks = 0; ks < 2; ++ks) {
;             const unsigned fo = ks ? fo1 : fo0;
;             bf16x8 af[4], bfr[4];
; #pragma unroll
;             for (int i = 0; i < 4; ++i) { af[i] = *(const LAS bf16x8*)(base + aoff + i * 2048 + fo); bfr[i] = *(const LAS bf16x8*)(base + boff + i * 2048 + fo); }
;             if (ks == 1 && more) { if (pf) asm volatile("s_waitcnt vmcnt(3)" ::: "memory"); else asm volatile("s_waitcnt vmcnt(0)" ::: "memory"); }
;             if (pf) { PIECE(s2, ks * 3 + 0); PIECE(s2, ks * 3 + 1); PIECE(s2, ks * 3 + 2); }
;             asm volatile("s_waitcnt lgkmcnt(0)" ::: "memory");
;             BAR();
;             __builtin_amdgcn_s_setprio(1);
; #pragma unroll
;             for (int mi = 0; mi < 4; ++mi)
; #pragma unroll
;                 for (int ni = 0; ni < 4; ++ni) acc[mi][ni] = __builtin_amdgcn_mfma_f32_16x16x32_bf16(bfr[ni], af[mi], acc[mi][ni], 0, 0, 0);
;             __builtin_amdgcn_s_setprio(0);
;             BAR();
;         }
;         st = st == 2 ? 0 : st + 1;
;     }
;     if (grp == 0) BAR();
	ds_read_b128 v[0:3], v188 offset:32784
	ds_read_b128 v[4:7], v189 offset:32784
	ds_read_b128 v[8:11], v188 offset:34832
	ds_read_b128 v[12:15], v189 offset:34832
	ds_read_b128 v[196:199], v188 offset:49168
	ds_read_b128 v[200:203], v189 offset:49168
	ds_read_b128 v[204:207], v188 offset:51216
	ds_read_b128 v[208:211], v189 offset:51216
	ds_read_b128 v[152:155], v186 offset:32784
	ds_read_b128 v[156:159], v187 offset:32784
	ds_read_b128 v[160:163], v186 offset:34832
	ds_read_b128 v[164:167], v187 offset:34832
	ds_read_b128 v[168:171], v186 offset:36880
	ds_read_b128 v[172:175], v187 offset:36880
	ds_read_b128 v[176:179], v186 offset:38928
	ds_read_b128 v[180:183], v187 offset:38928
	s_waitcnt lgkmcnt(0)
	s_waitcnt vmcnt(0)
	s_barrier
	s_setprio 1
	v_mfma_f32_16x16x32_bf16 v[24:27], v[0:3], v[152:155], v[24:27]
	v_mfma_f32_16x16x32_bf16 v[28:31], v[8:11], v[152:155], v[28:31]
	v_mfma_f32_16x16x32_bf16 v[32:35], v[0:3], v[160:163], v[32:35]
	v_mfma_f32_16x16x32_bf16 v[36:39], v[8:11], v[160:163], v[36:39]
	v_mfma_f32_16x16x32_bf16 v[40:43], v[0:3], v[168:171], v[40:43]
	v_mfma_f32_16x16x32_bf16 v[44:47], v[8:11], v[168:171], v[44:47]
	v_mfma_f32_16x16x32_bf16 v[48:51], v[0:3], v[176:179], v[48:51]
	v_mfma_f32_16x16x32_bf16 v[52:55], v[8:11], v[176:179], v[52:55]
	v_mfma_f32_16x16x32_bf16 v[24:27], v[4:7], v[156:159], v[24:27]
	v_mfma_f32_16x16x32_bf16 v[28:31], v[12:15], v[156:159], v[28:31]
	v_mfma_f32_16x16x32_bf16 v[32:35], v[4:7], v[164:167], v[32:35]
	v_mfma_f32_16x16x32_bf16 v[36:39], v[12:15], v[164:167], v[36:39]
	v_mfma_f32_16x16x32_bf16 v[40:43], v[4:7], v[172:175], v[40:43]
	v_mfma_f32_16x16x32_bf16 v[44:47], v[12:15], v[172:175], v[44:47]
	v_mfma_f32_16x16x32_bf16 v[48:51], v[4:7], v[180:183], v[48:51]
	v_mfma_f32_16x16x32_bf16 v[52:55], v[12:15], v[180:183], v[52:55]
	v_mfma_f32_16x16x32_bf16 v[56:59], v[196:199], v[152:155], v[56:59]
	v_mfma_f32_16x16x32_bf16 v[60:63], v[204:207], v[152:155], v[60:63]
	v_mfma_f32_16x16x32_bf16 v[64:67], v[196:199], v[160:163], v[64:67]
	v_mfma_f32_16x16x32_bf16 v[68:71], v[204:207], v[160:163], v[68:71]
	v_mfma_f32_16x16x32_bf16 v[72:75], v[196:199], v[168:171], v[72:75]
	v_mfma_f32_16x16x32_bf16 v[76:79], v[204:207], v[168:171], v[76:79]
	v_mfma_f32_16x16x32_bf16 v[80:83], v[196:199], v[176:179], v[80:83]
	v_mfma_f32_16x16x32_bf16 v[84:87], v[204:207], v[176:179], v[84:87]
	v_mfma_f32_16x16x32_bf16 v[56:59], v[200:203], v[156:159], v[56:59]
	v_mfma_f32_16x16x32_bf16 v[60:63], v[208:211], v[156:159], v[60:63]
	v_mfma_f32_16x16x32_bf16 v[64:67], v[200:203], v[164:167], v[64:67]
	v_mfma_f32_16x16x32_bf16 v[68:71], v[208:211], v[164:167], v[68:71]
	v_mfma_f32_16x16x32_bf16 v[72:75], v[200:203], v[172:175], v[72:75]
	v_mfma_f32_16x16x32_bf16 v[76:79], v[208:211], v[172:175], v[76:79]
	v_mfma_f32_16x16x32_bf16 v[80:83], v[200:203], v[180:183], v[80:83]
	v_mfma_f32_16x16x32_bf16 v[84:87], v[208:211], v[180:183], v[84:87]
	s_setprio 0
	s_barrier
	ds_read_b128 v[152:155], v186 offset:49168
	ds_read_b128 v[156:159], v187 offset:49168
	ds_read_b128 v[160:163], v186 offset:51216
	ds_read_b128 v[164:167], v187 offset:51216
	ds_read_b128 v[168:171], v186 offset:53264
	ds_read_b128 v[172:175], v187 offset:53264
	ds_read_b128 v[176:179], v186 offset:55312
	ds_read_b128 v[180:183], v187 offset:55312
	s_waitcnt lgkmcnt(0)
	s_barrier
	s_setprio 1
	v_mfma_f32_16x16x32_bf16 v[88:91], v[0:3], v[152:155], v[88:91]
	v_mfma_f32_16x16x32_bf16 v[92:95], v[8:11], v[152:155], v[92:95]
	v_mfma_f32_16x16x32_bf16 v[96:99], v[0:3], v[160:163], v[96:99]
	v_mfma_f32_16x16x32_bf16 v[100:103], v[8:11], v[160:163], v[100:103]
	v_mfma_f32_16x16x32_bf16 v[104:107], v[0:3], v[168:171], v[104:107]
	v_mfma_f32_16x16x32_bf16 v[108:111], v[8:11], v[168:171], v[108:111]
	v_mfma_f32_16x16x32_bf16 v[112:115], v[0:3], v[176:179], v[112:115]
	v_mfma_f32_16x16x32_bf16 v[116:119], v[8:11], v[176:179], v[116:119]
	v_mfma_f32_16x16x32_bf16 v[88:91], v[4:7], v[156:159], v[88:91]
	v_mfma_f32_16x16x32_bf16 v[92:95], v[12:15], v[156:159], v[92:95]
	v_mfma_f32_16x16x32_bf16 v[96:99], v[4:7], v[164:167], v[96:99]
	v_mfma_f32_16x16x32_bf16 v[100:103], v[12:15], v[164:167], v[100:103]
	v_mfma_f32_16x16x32_bf16 v[104:107], v[4:7], v[172:175], v[104:107]
	v_mfma_f32_16x16x32_bf16 v[108:111], v[12:15], v[172:175], v[108:111]
	v_mfma_f32_16x16x32_bf16 v[112:115], v[4:7], v[180:183], v[112:115]
	v_mfma_f32_16x16x32_bf16 v[116:119], v[12:15], v[180:183], v[116:119]
	v_mfma_f32_16x16x32_bf16 v[120:123], v[196:199], v[152:155], v[120:123]
	v_mfma_f32_16x16x32_bf16 v[124:127], v[204:207], v[152:155], v[124:127]
	v_mfma_f32_16x16x32_bf16 v[128:131], v[196:199], v[160:163], v[128:131]
	v_mfma_f32_16x16x32_bf16 v[132:135], v[204:207], v[160:163], v[132:135]
	v_mfma_f32_16x16x32_bf16 v[136:139], v[196:199], v[168:171], v[136:139]
	v_mfma_f32_16x16x32_bf16 v[140:143], v[204:207], v[168:171], v[140:143]
	v_mfma_f32_16x16x32_bf16 v[144:147], v[196:199], v[176:179], v[144:147]
	v_mfma_f32_16x16x32_bf16 v[148:151], v[204:207], v[176:179], v[148:151]
	v_mfma_f32_16x16x32_bf16 v[120:123], v[200:203], v[156:159], v[120:123]
	v_mfma_f32_16x16x32_bf16 v[124:127], v[208:211], v[156:159], v[124:127]
	v_mfma_f32_16x16x32_bf16 v[128:131], v[200:203], v[164:167], v[128:131]
	v_mfma_f32_16x16x32_bf16 v[132:135], v[208:211], v[164:167], v[132:135]
	v_mfma_f32_16x16x32_bf16 v[136:139], v[200:203], v[172:175], v[136:139]
	v_mfma_f32_16x16x32_bf16 v[140:143], v[208:211], v[172:175], v[140:143]
	v_mfma_f32_16x16x32_bf16 v[144:147], v[200:203], v[180:183], v[144:147]
	v_mfma_f32_16x16x32_bf16 v[148:151], v[208:211], v[180:183], v[148:151]
	s_setprio 0
	s_barrier
	s_cmp_lg_u32 s33, 0
	s_cbranch_scc1 .Lgyd_epi
	s_barrier

; #define BAR() { __builtin_amdgcn_sched_barrier(0); __builtin_amdgcn_s_barrier(); asm volatile("" ::: "memory"); __builtin_amdgcn_sched_barrier(0); }
; DI void gemm_stream2(const bf16_t* __restrict__ A, int lda, const bf16_t* __restrict__ Bt, int ldb, int K, int m0, int n0, ...
;     ...
;     const int wave = __builtin_amdgcn_readfirstlane(tid >> 6), lane = tid & 63, wm = wave >> 1, wn = wave & 1, r = lane & 15, q = lane >> 4;
;     const int sc0 = ((lane & 7) ^ (lane >> 4)) * 8, sc1 = ((lane & 7) ^ (4 | (lane >> 4))) * 8;
;     const bf16_t* ga = A + (size_t)(m0 + wave * 32 + (lane >> 3)) * lda;
;     const bf16_t* gb = Bt + (size_t)(n0 + wave * 16 + (lane >> 3)) * ldb;
;     const bf16_t* gan = An + (size_t)(m0n + wave * 32 + (lane >> 3)) * ldan;
;     const bf16_t* gbn = Btn + (size_t)(n0n + wave * 16 + (lane >> 3)) * ldbn;
;     const unsigned wa = (unsigned)wave * 4096u, wbb = 32768u + (unsigned)wave * 2048u;
;     ...
;     const int sw = r >> 1;
;     const unsigned fo0 = (unsigned)(r * 128 + ((q ^ sw) << 4)), fo1 = (unsigned)(r * 128 + (((q ^ sw) ^ 4) << 4));
;     const unsigned aoff = (unsigned)(wm * 64) * 128u, boff = 32768u + (unsigned)(wn * 64) * 128u;
;     const int nk = K / 64;
;     const int grp = wave >> 2;
;     ...
;     int st = rg.st;
;     if (!rg.primed) {
;         const int s1p = st == 2 ? 0 : st + 1;
;         BAR();
;         STAGE(st, 0);
;         STAGE(s1p, 1);
;         asm volatile("s_waitcnt vmcnt(6)" ::: "memory");
;         BAR();
;     }
;     if (grp == 1) BAR();
; DI void gemm_y(const Params& p, const bf16_t* A, int lda, size_t woff, int K, int kper, int bid, int nb, char* smem, const int tid) {
;     ...
;     for (; have; tm = tm2, tn = tn2) {
;         have = ti.next(tm2, tn2);
;         const int m0 = tm * 256, n0 = tn * 128;
;         f32x4 acc[4][4]; zero_acc(acc);
;         gemm_stream(A, lda, Bt, K, K, m0, n0, have, tm2 * 256, tn2 * 128, smem, acc, tid, rg);
.Lgyo_lanes:
	v_and_b32_e32 v190, 63, v193
	v_and_b32_e32 v191, 15, v190
	v_lshrrev_b32_e32 v17, 4, v190
	v_lshrrev_b32_e32 v18, 3, v190
	v_and_b32_e32 v19, 7, v190
	v_xor_b32_e32 v195, v19, v17
	v_lshlrev_b32_e32 v195, 4, v195
	s_mov_b32 s1, 0x800
	v_mad_u32_u24 v184, v18, s1, v195
	v_or_b32_e32 v195, 4, v17
	v_xor_b32_e32 v195, v19, v195
	v_lshlrev_b32_e32 v195, 4, v195
	v_add_u32_e32 v227, 8, v18
	v_mad_u32_u24 v185, v227, s1, v195
	v_lshrrev_b32_e32 v195, 1, v191
	v_xor_b32_e32 v195, v17, v195
	v_lshlrev_b32_e32 v195, 4, v195
	s_lshl_b32 s1, s33, 6
	v_add_u32_e32 v227, s1, v191
	v_lshl_add_u32 v186, v227, 7, v195
	v_xor_b32_e32 v187, 64, v186
	v_lshlrev_b32_e32 v228, 11, v227
	s_lshl_b32 s1, s36, 5
	v_add_u32_e32 v227, s1, v191
	v_lshl_add_u32 v188, v227, 7, v195
	v_add_u32_e32 v188, 0x10000, v188
	v_xor_b32_e32 v189, 64, v188
	s_lshl_b32 s1, s36, 6
	v_lshl_add_u32 v229, v17, 3, s1
	v_add_u32_e32 v237, v228, v229
	s_add_i32 m0, s39, 0x10000
	s_nop 0
	global_load_lds_dwordx4 v184, s[70:71]
	s_add_i32 m0, s39, 0x10400
	s_nop 0
	global_load_lds_dwordx4 v185, s[70:71]
	s_add_u32 s70, s70, 0x80
	s_addc_u32 s71, s71, 0
	s_add_i32 m0, s39, 0x0
	s_nop 0
	global_load_lds_dwordx4 v184, s[66:67]
	s_add_i32 m0, s39, 0x400
	s_nop 0
	global_load_lds_dwordx4 v185, s[66:67]
	s_add_u32 s66, s66, 0x80
	s_addc_u32 s67, s67, 0
	s_add_i32 m0, s39, 0x14000
	s_nop 0
	global_load_lds_dwordx4 v184, s[72:73]
	s_add_i32 m0, s39, 0x14400
	s_nop 0
	global_load_lds_dwordx4 v185, s[72:73]
	s_add_u32 s72, s72, 0x80
	s_addc_u32 s73, s73, 0
	s_add_i32 m0, s39, 0x4000
	s_nop 0
	global_load_lds_dwordx4 v184, s[68:69]
	s_add_i32 m0, s39, 0x4400
	s_nop 0
	global_load_lds_dwordx4 v185, s[68:69]
	s_add_u32 s68, s68, 0x80
	s_addc_u32 s69, s69, 0
	s_add_i32 m0, s39, 0x18000
	s_nop 0
	global_load_lds_dwordx4 v184, s[70:71]
	s_add_i32 m0, s39, 0x18400
	s_nop 0
	global_load_lds_dwordx4 v185, s[70:71]
	s_add_u32 s70, s70, 0x80
	s_addc_u32 s71, s71, 0
	s_add_i32 m0, s39, 0x8000
	s_nop 0
	global_load_lds_dwordx4 v184, s[66:67]
	s_add_i32 m0, s39, 0x8400
	s_nop 0
	global_load_lds_dwordx4 v185, s[66:67]
	s_add_u32 s66, s66, 0x80
	s_addc_u32 s67, s67, 0
	s_add_i32 m0, s39, 0x1c000
	s_nop 0
	global_load_lds_dwordx4 v184, s[72:73]
	s_add_i32 m0, s39, 0x1c400
	s_nop 0
	global_load_lds_dwordx4 v185, s[72:73]
	s_add_u32 s72, s72, 0x80
	s_addc_u32 s73, s73, 0
	s_waitcnt vmcnt(8)
	s_barrier
	s_cmp_eq_u32 s33, 0
	s_cbranch_scc1 .Lgyo_lead
	s_barrier
.Lgyo_lead:
.Lgyo_item:
	s_cmp_eq_u32 s55, 0
	s_cbranch_scc0 .Lgyo_nx_unit
	s_add_u32 s76, s51, s53
	s_cmp_lt_u32 s76, s52
	s_cbranch_scc0 .Lgyo_nx_first_unit
	s_mov_b32 s54, 1
	s_mov_b32 s93, 0
	s_lshr_b32 s1, s76, 5
	s_and_b32 s2, s76, 31
	s_lshr_b32 s60, s2, 3
	s_and_b32 s2, s2, 7
	s_lshl_b32 s1, s1, 3
	s_add_i32 s59, s1, s2
	s_mul_i32 s2, s10, 0x8000
	s_mul_i32 s1, s59, 0x80000
	s_add_u32 s1, s1, s2
	s_add_u32 s74, s88, s1
	s_addc_u32 s75, s89, 0
	s_add_u32 s74, s74, 0x3240000
	s_addc_u32 s75, s75, 0
	s_add_u32 s78, s74, 0x40000
	s_addc_u32 s79, s75, 0
	s_mul_i32 s1, s60, 0x80000
	s_add_u32 s1, s1, s2
	s_add_u32 s1, s1, s61
	s_add_u32 s80, s88, s1
	s_addc_u32 s81, s89, 0
	s_add_u32 s82, s80, 0x40000
	s_addc_u32 s83, s81, 0
	s_branch .Lgyo_nx_done
